# v17 plus peeled first K-iteration using C=0 MFMAs (no accumulator zeroing)
# baseline (speedup 1.0000x reference)
; #define PG8_STAGE(bufoff, gbase, voff) do { _Pragma("unroll") for (int _i = 0; _i < 2; ++_i) \
;         __builtin_amdgcn_global_load_lds((const unsigned*)((const char*)(gbase) + (voff)[_i]), (LAS unsigned*)(lds + (bufoff) + ldsw + _i * 8192), 16, 0, 0); } while (0)
; #define PG8_LDA(dst, b, h) do { _Pragma("unroll") for (int m = 0; m < 4; ++m) _Pragma("unroll") for (int k = 0; k < 2; ++k) dst[m][k] = *(const LAS bf16x8*)(lds + PG8_SA(b, h) + aoff + m * 2048 + k * 1024); } while (0)
; #define PG8_LDB(dst, b, h) do { _Pragma("unroll") for (int n = 0; n < 2; ++n) _Pragma("unroll") for (int k = 0; k < 2; ++k) dst[n][k] = *(const LAS bf16x8*)(lds + PG8_SB(b, h) + boff + n * 2048 + k * 1024); } while (0)
; #define PG8_MMA(ai, bj, At, Bt) do { __builtin_amdgcn_s_setprio(1); _Pragma("unroll") for (int m = 0; m < 4; ++m) _Pragma("unroll") for (int n = 0; n < 2; ++n) _Pragma("unroll") for (int k = 0; k < 2; ++k) \
;         acc[ai][bj][m][n] = __builtin_amdgcn_mfma_f32_16x16x32_bf16(Bt[n][k], At[m][k], acc[ai][bj][m][n], 0, 0, 0); __builtin_amdgcn_s_setprio(0); } while (0)
; template <class Epi>
; __device__ __forceinline__ void gemm_phase(LAS unsigned char* lds, const Gemm g, const StaticOrder& S, const Epi& E) {
;     ...
;         const bool has_next = S.next(ui + 1, nxt);
;         const char* nA = has_next ? (const char*)g.A + (size_t)nxt.pm * tstep : cA; const char* nB = has_next ? (const char*)g.Bt + (size_t)nxt.pn * tstep : cB;
;         for (int t = 0; t < nt; t += 2) {
;             const bool last = (t == nt - 2);
;             const char* a1 = cA + (size_t)(t + 1) * kstepA;
;             const char* a2 = last ? nA : cA + (size_t)(t + 2) * kstepA; const char* b2 = last ? nB : cB + (size_t)(t + 2) * kstepB;
;             const char* a3 = a2 + kstepA; const char* b3 = b2 + kstepB;
;             PG8_LDB(B0, 0, 0); PG8_SCHED; PG8_LDA(At, 0, 0); PG8_STAGE(PG8_SA(1, 1), a1 + hstep, voffA);
;             PG8_WAIT_L(8); PG8_BAR; PG8_WAIT_L(0); PG8_MMA(0, 0, At, B0); PG8_BAR; PG8_SCHED;
;             PG8_LDB(B1, 0, 1); PG8_STAGE(PG8_SB(0, 0), b2, voffB);
;             PG8_BAR; PG8_WAIT_L(0); PG8_MMA(0, 1, At, B1); PG8_BAR;
;             PG8_LDA(At, 0, 1); PG8_STAGE(PG8_SA(0, 0), a2, voffA);
;             PG8_BAR; PG8_WAIT_L(0); PG8_MMA(1, 0, At, B0); PG8_BAR; PG8_SCHED;
;             PG8_STAGE(PG8_SB(0, 1), b2 + hstep, voffB);
.LBB0_209:
	s_ashr_i32 s7, s6, 31
	v_cmp_lt_i64_e32 vcc, s[8:9], v[138:139]
	s_lshl_b64 s[8:9], s[6:7], 15
	s_add_u32 s8, s88, s8
	s_addc_u32 s9, s89, s9
	s_and_b64 s[10:11], vcc, exec
	s_cselect_b32 s7, s9, s31
	s_cselect_b32 s56, s8, s30
	s_ashr_i32 s5, s4, 31
	s_lshl_b64 s[10:11], s[4:5], 15
	s_add_u32 s10, s80, s10
	s_addc_u32 s11, s81, s11
	s_and_b64 s[34:35], vcc, exec
	s_cselect_b32 s5, s11, s29
	s_cselect_b32 s57, s10, s28
	s_add_u32 s58, s28, 0x2c0000
	s_addc_u32 s59, s29, 0
	s_add_u32 s28, s30, 0x404000
	v_mov_b32_e32 v0, 0
	s_addc_u32 s29, s31, 0
	s_mov_b32 s60, -2
	ds_read_b128 v[156:159], v152
	ds_read_b128 v[160:163], v152 offset:1024
	ds_read_b128 v[164:167], v152 offset:2048
	ds_read_b128 v[168:171], v152 offset:3072
	s_add_u32 s30, s28, 0x3fc000
	s_addc_u32 s31, s29, 0
	s_cmp_eq_u32 s60, 28
	s_cselect_b32 s36, s56, s30
	s_cselect_b32 s37, s7, s31
	s_cselect_b32 s30, s57, s58
	s_cselect_b32 s31, s5, s59
	s_add_u32 s34, s36, 0x400000
	s_addc_u32 s35, s37, 0
	v_lshl_add_u64 v[142:143], s[28:29], 0, v[134:135]
	s_add_i32 m0, s42, 0xc000
	ds_read_b128 v[172:175], v153
	ds_read_b128 v[176:179], v153 offset:1024
	ds_read_b128 v[184:187], v153 offset:2048
	ds_read_b128 v[188:191], v153 offset:3072
	ds_read_b128 v[192:195], v153 offset:4096
	ds_read_b128 v[196:199], v153 offset:5120
	ds_read_b128 v[200:203], v153 offset:6144
	ds_read_b128 v[204:207], v153 offset:7168
	global_load_lds_dwordx4 v[142:143], off
	v_lshl_add_u64 v[142:143], s[28:29], 0, v[136:137]
	s_add_i32 m0, s42, 0xe000
	s_nop 0
	global_load_lds_dwordx4 v[142:143], off
	ds_read_b128 v[208:211], v154
	ds_read_b128 v[212:215], v154 offset:1024
	ds_read_b128 v[216:219], v154 offset:2048
	ds_read_b128 v[220:223], v154 offset:3072
	s_waitcnt lgkmcnt(0)
	s_waitcnt vmcnt(8)
	s_barrier
	s_nop 0
	v_mfma_f32_16x16x32_bf16 v[124:127], v[156:159], v[172:175], 0
	v_mfma_f32_16x16x32_bf16 v[120:123], v[164:167], v[172:175], 0
	v_mfma_f32_16x16x32_bf16 v[108:111], v[156:159], v[184:187], 0
	v_mfma_f32_16x16x32_bf16 v[104:107], v[164:167], v[184:187], 0
	v_mfma_f32_16x16x32_bf16 v[92:95], v[156:159], v[192:195], 0
	v_mfma_f32_16x16x32_bf16 v[88:91], v[164:167], v[192:195], 0
	v_mfma_f32_16x16x32_bf16 v[76:79], v[156:159], v[200:203], 0
	v_mfma_f32_16x16x32_bf16 v[72:75], v[164:167], v[200:203], 0
	v_mfma_f32_16x16x32_bf16 v[124:127], v[160:163], v[176:179], v[124:127]
	v_mfma_f32_16x16x32_bf16 v[120:123], v[168:171], v[176:179], v[120:123]
	v_mfma_f32_16x16x32_bf16 v[108:111], v[160:163], v[188:191], v[108:111]
	v_mfma_f32_16x16x32_bf16 v[104:107], v[168:171], v[188:191], v[104:107]
	v_mfma_f32_16x16x32_bf16 v[92:95], v[160:163], v[196:199], v[92:95]
	v_mfma_f32_16x16x32_bf16 v[88:91], v[168:171], v[196:199], v[88:91]
	v_mfma_f32_16x16x32_bf16 v[76:79], v[160:163], v[204:207], v[76:79]
	v_mfma_f32_16x16x32_bf16 v[72:75], v[168:171], v[204:207], v[72:75]
	v_mfma_f32_16x16x32_bf16 v[116:119], v[208:211], v[172:175], 0
	v_mfma_f32_16x16x32_bf16 v[112:115], v[216:219], v[172:175], 0
	v_mfma_f32_16x16x32_bf16 v[100:103], v[208:211], v[184:187], 0
	v_mfma_f32_16x16x32_bf16 v[96:99], v[216:219], v[184:187], 0
	v_mfma_f32_16x16x32_bf16 v[84:87], v[208:211], v[192:195], 0
	v_mfma_f32_16x16x32_bf16 v[80:83], v[216:219], v[192:195], 0
	v_mfma_f32_16x16x32_bf16 v[68:71], v[208:211], v[200:203], 0
	v_mfma_f32_16x16x32_bf16 v[64:67], v[216:219], v[200:203], 0
	v_mfma_f32_16x16x32_bf16 v[116:119], v[212:215], v[176:179], v[116:119]
	v_mfma_f32_16x16x32_bf16 v[112:115], v[220:223], v[176:179], v[112:115]
	v_mfma_f32_16x16x32_bf16 v[100:103], v[212:215], v[188:191], v[100:103]
	v_mfma_f32_16x16x32_bf16 v[96:99], v[220:223], v[188:191], v[96:99]
	v_mfma_f32_16x16x32_bf16 v[84:87], v[212:215], v[196:199], v[84:87]
	v_mfma_f32_16x16x32_bf16 v[80:83], v[220:223], v[196:199], v[80:83]
	v_mfma_f32_16x16x32_bf16 v[68:71], v[212:215], v[204:207], v[68:71]
	v_mfma_f32_16x16x32_bf16 v[64:67], v[220:223], v[204:207], v[64:67]
	s_nop 0
	s_barrier
	s_add_i32 s61, s54, s39
	v_lshl_add_u64 v[142:143], s[30:31], 0, v[130:131]
	s_mov_b32 m0, s61
	s_nop 0
	global_load_lds_dwordx4 v[142:143], off
	v_lshl_add_u64 v[142:143], s[30:31], 0, v[128:129]
	s_add_i32 m0, s61, 0x2000
	s_nop 0
	global_load_lds_dwordx4 v[142:143], off
	s_mov_b32 m0, s42
	v_lshl_add_u64 v[142:143], s[36:37], 0, v[130:131]
	ds_read_b128 v[172:175], v153 offset:16384
	ds_read_b128 v[176:179], v153 offset:17408
	ds_read_b128 v[184:187], v153 offset:18432
	ds_read_b128 v[188:191], v153 offset:19456
	ds_read_b128 v[192:195], v153 offset:20480
	ds_read_b128 v[196:199], v153 offset:21504
	ds_read_b128 v[200:203], v153 offset:22528
	ds_read_b128 v[204:207], v153 offset:23552
	global_load_lds_dwordx4 v[142:143], off
	v_lshl_add_u64 v[142:143], s[36:37], 0, v[128:129]
	s_mov_b32 m0, s43
	s_nop 0
	global_load_lds_dwordx4 v[142:143], off
	s_add_u32 s94, s30, 0x4000
	s_addc_u32 s95, s31, 0
	s_add_i32 s61, s55, s39
	v_lshl_add_u64 v[142:143], s[94:95], 0, v[130:131]
	s_mov_b32 m0, s61
	s_nop 0
	global_load_lds_dwordx4 v[142:143], off
	v_lshl_add_u64 v[142:143], s[94:95], 0, v[128:129]
	s_add_i32 m0, s61, 0x2000
	s_nop 0
	global_load_lds_dwordx4 v[142:143], off
	s_waitcnt lgkmcnt(0)
	s_waitcnt vmcnt(8)
	s_barrier
; #define PG8_STAGE(bufoff, gbase, voff) do { _Pragma("unroll") for (int _i = 0; _i < 2; ++_i) \
;         __builtin_amdgcn_global_load_lds((const unsigned*)((const char*)(gbase) + (voff)[_i]), (LAS unsigned*)(lds + (bufoff) + ldsw + _i * 8192), 16, 0, 0); } while (0)
; #define PG8_LDA(dst, b, h) do { _Pragma("unroll") for (int m = 0; m < 4; ++m) _Pragma("unroll") for (int k = 0; k < 2; ++k) dst[m][k] = *(const LAS bf16x8*)(lds + PG8_SA(b, h) + aoff + m * 2048 + k * 1024); } while (0)
; #define PG8_LDB(dst, b, h) do { _Pragma("unroll") for (int n = 0; n < 2; ++n) _Pragma("unroll") for (int k = 0; k < 2; ++k) dst[n][k] = *(const LAS bf16x8*)(lds + PG8_SB(b, h) + boff + n * 2048 + k * 1024); } while (0)
; #define PG8_MMA(ai, bj, At, Bt) do { __builtin_amdgcn_s_setprio(1); _Pragma("unroll") for (int m = 0; m < 4; ++m) _Pragma("unroll") for (int n = 0; n < 2; ++n) _Pragma("unroll") for (int k = 0; k < 2; ++k) \
;         acc[ai][bj][m][n] = __builtin_amdgcn_mfma_f32_16x16x32_bf16(Bt[n][k], At[m][k], acc[ai][bj][m][n], 0, 0, 0); __builtin_amdgcn_s_setprio(0); } while (0)
; #define PG8_WAIT_V(n) asm volatile("s_waitcnt vmcnt(" #n ")" ::: "memory")
; #define PG8_WAIT_L(n) asm volatile("s_waitcnt lgkmcnt(" #n ")" ::: "memory")
; #define PG8_BAR __builtin_amdgcn_s_barrier()
; #define PG8_SCHED __builtin_amdgcn_sched_barrier(0)
; template <class Epi>
; __device__ __forceinline__ void gemm_phase(LAS unsigned char* lds, const Gemm g, const StaticOrder& S, const Epi& E) {
;     ...
;             PG8_BAR; PG8_WAIT_L(0); PG8_MMA(1, 0, At, B0); PG8_BAR; PG8_SCHED;
;             PG8_STAGE(PG8_SB(0, 1), b2 + hstep, voffB);
;             PG8_WAIT_V(6); PG8_BAR; PG8_MMA(1, 1, At, B1); PG8_BAR;
;             PG8_LDB(B0, 1, 0); PG8_SCHED; PG8_LDA(At, 1, 0); PG8_STAGE(PG8_SA(0, 1), a2 + hstep, voffA);
;             PG8_WAIT_L(8); PG8_BAR; PG8_WAIT_L(0); PG8_MMA(0, 0, At, B0); PG8_BAR; PG8_SCHED;
;             PG8_LDB(B1, 1, 1); PG8_STAGE(PG8_SB(1, 0), b3, voffB);
;             PG8_BAR; PG8_WAIT_L(0); PG8_MMA(0, 1, At, B1); PG8_BAR;
	s_nop 0
	v_mfma_f32_16x16x32_bf16 v[60:63], v[156:159], v[172:175], 0
	v_mfma_f32_16x16x32_bf16 v[56:59], v[164:167], v[172:175], 0
	v_mfma_f32_16x16x32_bf16 v[44:47], v[156:159], v[184:187], 0
	v_mfma_f32_16x16x32_bf16 v[40:43], v[164:167], v[184:187], 0
	v_mfma_f32_16x16x32_bf16 v[28:31], v[156:159], v[192:195], 0
	v_mfma_f32_16x16x32_bf16 v[24:27], v[164:167], v[192:195], 0
	v_mfma_f32_16x16x32_bf16 v[12:15], v[156:159], v[200:203], 0
	v_mfma_f32_16x16x32_bf16 v[8:11], v[164:167], v[200:203], 0
	v_mfma_f32_16x16x32_bf16 v[60:63], v[160:163], v[176:179], v[60:63]
	v_mfma_f32_16x16x32_bf16 v[56:59], v[168:171], v[176:179], v[56:59]
	v_mfma_f32_16x16x32_bf16 v[44:47], v[160:163], v[188:191], v[44:47]
	v_mfma_f32_16x16x32_bf16 v[40:43], v[168:171], v[188:191], v[40:43]
	v_mfma_f32_16x16x32_bf16 v[28:31], v[160:163], v[196:199], v[28:31]
	v_mfma_f32_16x16x32_bf16 v[24:27], v[168:171], v[196:199], v[24:27]
	v_mfma_f32_16x16x32_bf16 v[12:15], v[160:163], v[204:207], v[12:15]
	v_mfma_f32_16x16x32_bf16 v[8:11], v[168:171], v[204:207], v[8:11]
	v_mfma_f32_16x16x32_bf16 v[52:55], v[208:211], v[172:175], 0
	v_mfma_f32_16x16x32_bf16 v[48:51], v[216:219], v[172:175], 0
	v_mfma_f32_16x16x32_bf16 v[36:39], v[208:211], v[184:187], 0
	v_mfma_f32_16x16x32_bf16 v[32:35], v[216:219], v[184:187], 0
	v_mfma_f32_16x16x32_bf16 v[20:23], v[208:211], v[192:195], 0
	v_mfma_f32_16x16x32_bf16 v[16:19], v[216:219], v[192:195], 0
	v_mfma_f32_16x16x32_bf16 v[4:7], v[208:211], v[200:203], 0
	v_mfma_f32_16x16x32_bf16 v[0:3], v[216:219], v[200:203], 0
	v_mfma_f32_16x16x32_bf16 v[52:55], v[212:215], v[176:179], v[52:55]
	v_mfma_f32_16x16x32_bf16 v[48:51], v[220:223], v[176:179], v[48:51]
	v_mfma_f32_16x16x32_bf16 v[36:39], v[212:215], v[188:191], v[36:39]
	v_mfma_f32_16x16x32_bf16 v[32:35], v[220:223], v[188:191], v[32:35]
	v_mfma_f32_16x16x32_bf16 v[20:23], v[212:215], v[196:199], v[20:23]
	v_mfma_f32_16x16x32_bf16 v[16:19], v[220:223], v[196:199], v[16:19]
	v_mfma_f32_16x16x32_bf16 v[4:7], v[212:215], v[204:207], v[4:7]
	v_mfma_f32_16x16x32_bf16 v[0:3], v[220:223], v[204:207], v[0:3]
	s_nop 0
	s_add_i32 s61, 0, 0x18000
	v_add_u32_e32 v142, s61, v151
	s_barrier
	ds_read_b128 v[156:159], v142
	ds_read_b128 v[160:163], v142 offset:1024
	ds_read_b128 v[164:167], v142 offset:2048
	ds_read_b128 v[168:171], v142 offset:3072
	s_add_u32 s36, s36, 0x4000
	s_addc_u32 s37, s37, 0
	s_mov_b32 m0, s44
	v_lshl_add_u64 v[142:143], s[36:37], 0, v[130:131]
	ds_read_b128 v[172:175], v153 offset:32768
	ds_read_b128 v[176:179], v153 offset:33792
	ds_read_b128 v[184:187], v153 offset:34816
	ds_read_b128 v[188:191], v153 offset:35840
	ds_read_b128 v[192:195], v153 offset:36864
	ds_read_b128 v[196:199], v153 offset:37888
	ds_read_b128 v[200:203], v153 offset:38912
	ds_read_b128 v[204:207], v153 offset:39936
	global_load_lds_dwordx4 v[142:143], off
	v_lshl_add_u64 v[142:143], s[36:37], 0, v[128:129]
	s_mov_b32 m0, s45
	s_nop 0
	global_load_lds_dwordx4 v[142:143], off
	v_add_u32_e32 v253, 0x1c000, v151
	ds_read_b128 v[208:211], v253
	ds_read_b128 v[212:215], v253 offset:1024
	ds_read_b128 v[216:219], v253 offset:2048
	ds_read_b128 v[220:223], v253 offset:3072
	s_waitcnt lgkmcnt(0)
	s_waitcnt vmcnt(8)
	s_barrier
	s_nop 0
	v_mfma_f32_16x16x32_bf16 v[124:127], v[156:159], v[172:175], v[124:127]
	v_mfma_f32_16x16x32_bf16 v[120:123], v[164:167], v[172:175], v[120:123]
	v_mfma_f32_16x16x32_bf16 v[108:111], v[156:159], v[184:187], v[108:111]
	v_mfma_f32_16x16x32_bf16 v[104:107], v[164:167], v[184:187], v[104:107]
	v_mfma_f32_16x16x32_bf16 v[92:95], v[156:159], v[192:195], v[92:95]
	v_mfma_f32_16x16x32_bf16 v[88:91], v[164:167], v[192:195], v[88:91]
	v_mfma_f32_16x16x32_bf16 v[76:79], v[156:159], v[200:203], v[76:79]
	v_mfma_f32_16x16x32_bf16 v[72:75], v[164:167], v[200:203], v[72:75]
	v_mfma_f32_16x16x32_bf16 v[124:127], v[160:163], v[176:179], v[124:127]
	v_mfma_f32_16x16x32_bf16 v[120:123], v[168:171], v[176:179], v[120:123]
	v_mfma_f32_16x16x32_bf16 v[108:111], v[160:163], v[188:191], v[108:111]
	v_mfma_f32_16x16x32_bf16 v[104:107], v[168:171], v[188:191], v[104:107]
	v_mfma_f32_16x16x32_bf16 v[92:95], v[160:163], v[196:199], v[92:95]
	v_mfma_f32_16x16x32_bf16 v[88:91], v[168:171], v[196:199], v[88:91]
	v_mfma_f32_16x16x32_bf16 v[76:79], v[160:163], v[204:207], v[76:79]
	v_mfma_f32_16x16x32_bf16 v[72:75], v[168:171], v[204:207], v[72:75]
	v_mfma_f32_16x16x32_bf16 v[116:119], v[208:211], v[172:175], v[116:119]
	v_mfma_f32_16x16x32_bf16 v[112:115], v[216:219], v[172:175], v[112:115]
	v_mfma_f32_16x16x32_bf16 v[100:103], v[208:211], v[184:187], v[100:103]
	v_mfma_f32_16x16x32_bf16 v[96:99], v[216:219], v[184:187], v[96:99]
	v_mfma_f32_16x16x32_bf16 v[84:87], v[208:211], v[192:195], v[84:87]
	v_mfma_f32_16x16x32_bf16 v[80:83], v[216:219], v[192:195], v[80:83]
	v_mfma_f32_16x16x32_bf16 v[68:71], v[208:211], v[200:203], v[68:71]
	v_mfma_f32_16x16x32_bf16 v[64:67], v[216:219], v[200:203], v[64:67]
	v_mfma_f32_16x16x32_bf16 v[116:119], v[212:215], v[176:179], v[116:119]
	v_mfma_f32_16x16x32_bf16 v[112:115], v[220:223], v[176:179], v[112:115]
	v_mfma_f32_16x16x32_bf16 v[100:103], v[212:215], v[188:191], v[100:103]
	v_mfma_f32_16x16x32_bf16 v[96:99], v[220:223], v[188:191], v[96:99]
	v_mfma_f32_16x16x32_bf16 v[84:87], v[212:215], v[196:199], v[84:87]
	v_mfma_f32_16x16x32_bf16 v[80:83], v[220:223], v[196:199], v[80:83]
	v_mfma_f32_16x16x32_bf16 v[68:71], v[212:215], v[204:207], v[68:71]
	v_mfma_f32_16x16x32_bf16 v[64:67], v[220:223], v[204:207], v[64:67]
	s_nop 0
	s_barrier
; #define PG8_STAGE(bufoff, gbase, voff) do { _Pragma("unroll") for (int _i = 0; _i < 2; ++_i) \
;         __builtin_amdgcn_global_load_lds((const unsigned*)((const char*)(gbase) + (voff)[_i]), (LAS unsigned*)(lds + (bufoff) + ldsw + _i * 8192), 16, 0, 0); } while (0)
; #define PG8_LDA(dst, b, h) do { _Pragma("unroll") for (int m = 0; m < 4; ++m) _Pragma("unroll") for (int k = 0; k < 2; ++k) dst[m][k] = *(const LAS bf16x8*)(lds + PG8_SA(b, h) + aoff + m * 2048 + k * 1024); } while (0)
; #define PG8_MMA(ai, bj, At, Bt) do { __builtin_amdgcn_s_setprio(1); _Pragma("unroll") for (int m = 0; m < 4; ++m) _Pragma("unroll") for (int n = 0; n < 2; ++n) _Pragma("unroll") for (int k = 0; k < 2; ++k) \
;         acc[ai][bj][m][n] = __builtin_amdgcn_mfma_f32_16x16x32_bf16(Bt[n][k], At[m][k], acc[ai][bj][m][n], 0, 0, 0); __builtin_amdgcn_s_setprio(0); } while (0)
; #define PG8_WAIT_V(n) asm volatile("s_waitcnt vmcnt(" #n ")" ::: "memory")
; #define PG8_WAIT_L(n) asm volatile("s_waitcnt lgkmcnt(" #n ")" ::: "memory")
; #define PG8_BAR __builtin_amdgcn_s_barrier()
; #define PG8_SCHED __builtin_amdgcn_sched_barrier(0)
; template <class Epi>
; __device__ __forceinline__ void gemm_phase(LAS unsigned char* lds, const Gemm g, const StaticOrder& S, const Epi& E) {
;     ...
;             PG8_LDA(At, 1, 1); PG8_STAGE(PG8_SA(1, 0), a3, voffA);
;             PG8_BAR; PG8_WAIT_L(0); PG8_MMA(1, 0, At, B0); PG8_BAR; PG8_SCHED;
;             PG8_STAGE(PG8_SB(1, 1), b3 + hstep, voffB);
;             PG8_WAIT_V(6); PG8_BAR; PG8_MMA(1, 1, At, B1); PG8_BAR;
	s_add_i32 s63, 0, 0x1c000
	s_add_u32 s36, s30, 0x160000
	v_add_u32_e32 v142, s63, v151
	s_addc_u32 s37, s31, 0
	s_add_i32 s61, s61, s39
	s_nop 0
	v_lshl_add_u64 v[142:143], s[36:37], 0, v[130:131]
	s_mov_b32 m0, s61
	s_nop 0
	global_load_lds_dwordx4 v[142:143], off
	v_lshl_add_u64 v[142:143], s[36:37], 0, v[128:129]
	s_add_i32 m0, s61, 0x2000
	s_nop 0
	global_load_lds_dwordx4 v[142:143], off
	s_mov_b32 m0, s50
	v_lshl_add_u64 v[142:143], s[34:35], 0, v[130:131]
	ds_read_b128 v[172:175], v153 offset:49152
	ds_read_b128 v[176:179], v153 offset:50176
	ds_read_b128 v[184:187], v153 offset:51200
	ds_read_b128 v[188:191], v153 offset:52224
	ds_read_b128 v[192:195], v153 offset:53248
	ds_read_b128 v[196:199], v153 offset:54272
	ds_read_b128 v[200:203], v153 offset:55296
	ds_read_b128 v[204:207], v153 offset:56320
	global_load_lds_dwordx4 v[142:143], off
	v_lshl_add_u64 v[142:143], s[34:35], 0, v[128:129]
	s_mov_b32 m0, s51
	s_nop 0
	global_load_lds_dwordx4 v[142:143], off
	s_add_u32 s30, s30, 0x164000
	s_addc_u32 s31, s31, 0
	s_add_i32 s34, s63, s39
	v_lshl_add_u64 v[142:143], s[30:31], 0, v[130:131]
	s_mov_b32 m0, s34
	s_nop 0
	global_load_lds_dwordx4 v[142:143], off
	v_lshl_add_u64 v[142:143], s[30:31], 0, v[128:129]
	s_add_i32 m0, s34, 0x2000
	s_nop 0
	global_load_lds_dwordx4 v[142:143], off
	s_waitcnt lgkmcnt(0)
	s_waitcnt vmcnt(8)
	s_barrier
	s_nop 0
	v_mfma_f32_16x16x32_bf16 v[60:63], v[156:159], v[172:175], v[60:63]
	v_mfma_f32_16x16x32_bf16 v[56:59], v[164:167], v[172:175], v[56:59]
	v_mfma_f32_16x16x32_bf16 v[44:47], v[156:159], v[184:187], v[44:47]
	v_mfma_f32_16x16x32_bf16 v[40:43], v[164:167], v[184:187], v[40:43]
	v_mfma_f32_16x16x32_bf16 v[28:31], v[156:159], v[192:195], v[28:31]
	v_mfma_f32_16x16x32_bf16 v[24:27], v[164:167], v[192:195], v[24:27]
	v_mfma_f32_16x16x32_bf16 v[12:15], v[156:159], v[200:203], v[12:15]
	v_mfma_f32_16x16x32_bf16 v[8:11], v[164:167], v[200:203], v[8:11]
	v_mfma_f32_16x16x32_bf16 v[60:63], v[160:163], v[176:179], v[60:63]
	v_mfma_f32_16x16x32_bf16 v[56:59], v[168:171], v[176:179], v[56:59]
	v_mfma_f32_16x16x32_bf16 v[44:47], v[160:163], v[188:191], v[44:47]
	v_mfma_f32_16x16x32_bf16 v[40:43], v[168:171], v[188:191], v[40:43]
	v_mfma_f32_16x16x32_bf16 v[28:31], v[160:163], v[196:199], v[28:31]
	v_mfma_f32_16x16x32_bf16 v[24:27], v[168:171], v[196:199], v[24:27]
	v_mfma_f32_16x16x32_bf16 v[12:15], v[160:163], v[204:207], v[12:15]
	v_mfma_f32_16x16x32_bf16 v[8:11], v[168:171], v[204:207], v[8:11]
	v_mfma_f32_16x16x32_bf16 v[52:55], v[208:211], v[172:175], v[52:55]
	v_mfma_f32_16x16x32_bf16 v[48:51], v[216:219], v[172:175], v[48:51]
	v_mfma_f32_16x16x32_bf16 v[36:39], v[208:211], v[184:187], v[36:39]
	v_mfma_f32_16x16x32_bf16 v[32:35], v[216:219], v[184:187], v[32:35]
	v_mfma_f32_16x16x32_bf16 v[20:23], v[208:211], v[192:195], v[20:23]
	v_mfma_f32_16x16x32_bf16 v[16:19], v[216:219], v[192:195], v[16:19]
	v_mfma_f32_16x16x32_bf16 v[4:7], v[208:211], v[200:203], v[4:7]
	v_mfma_f32_16x16x32_bf16 v[0:3], v[216:219], v[200:203], v[0:3]
	v_mfma_f32_16x16x32_bf16 v[52:55], v[212:215], v[176:179], v[52:55]
	v_mfma_f32_16x16x32_bf16 v[48:51], v[220:223], v[176:179], v[48:51]
	v_mfma_f32_16x16x32_bf16 v[36:39], v[212:215], v[188:191], v[36:39]
	v_mfma_f32_16x16x32_bf16 v[32:35], v[220:223], v[188:191], v[32:35]
	v_mfma_f32_16x16x32_bf16 v[20:23], v[212:215], v[196:199], v[20:23]
	v_mfma_f32_16x16x32_bf16 v[16:19], v[220:223], v[196:199], v[16:19]
	v_mfma_f32_16x16x32_bf16 v[4:7], v[212:215], v[204:207], v[4:7]
	v_mfma_f32_16x16x32_bf16 v[0:3], v[220:223], v[204:207], v[0:3]
	s_nop 0
	s_add_i32 s60, s60, 2
	s_add_u32 s58, s58, 0x2c0000
	s_addc_u32 s59, s59, 0
	s_add_u32 s28, s28, 0x800000
	s_addc_u32 s29, s29, 0
	s_cmp_gt_u32 s60, 29
	s_barrier

; #define PG8_STAGE(bufoff, gbase, voff) do { _Pragma("unroll") for (int _i = 0; _i < 2; ++_i) \
;         __builtin_amdgcn_global_load_lds((const unsigned*)((const char*)(gbase) + (voff)[_i]), (LAS unsigned*)(lds + (bufoff) + ldsw + _i * 8192), 16, 0, 0); } while (0)
; #define PG8_LDA(dst, b, h) do { _Pragma("unroll") for (int m = 0; m < 4; ++m) _Pragma("unroll") for (int k = 0; k < 2; ++k) dst[m][k] = *(const LAS bf16x8*)(lds + PG8_SA(b, h) + aoff + m * 2048 + k * 1024); } while (0)
; #define PG8_LDB(dst, b, h) do { _Pragma("unroll") for (int n = 0; n < 2; ++n) _Pragma("unroll") for (int k = 0; k < 2; ++k) dst[n][k] = *(const LAS bf16x8*)(lds + PG8_SB(b, h) + boff + n * 2048 + k * 1024); } while (0)
; #define PG8_MMA(ai, bj, At, Bt) do { __builtin_amdgcn_s_setprio(1); _Pragma("unroll") for (int m = 0; m < 4; ++m) _Pragma("unroll") for (int n = 0; n < 2; ++n) _Pragma("unroll") for (int k = 0; k < 2; ++k) \
;         acc[ai][bj][m][n] = __builtin_amdgcn_mfma_f32_16x16x32_bf16(Bt[n][k], At[m][k], acc[ai][bj][m][n], 0, 0, 0); __builtin_amdgcn_s_setprio(0); } while (0)
; template <class Epi>
; __device__ __forceinline__ void gemm_phase(LAS unsigned char* lds, const Gemm g, const StaticOrder& S, const Epi& E) {
;     ...
;         const bool has_next = S.next(ui + 1, nxt);
;         const char* nA = has_next ? (const char*)g.A + (size_t)nxt.pm * tstep : cA; const char* nB = has_next ? (const char*)g.Bt + (size_t)nxt.pn * tstep : cB;
;         for (int t = 0; t < nt; t += 2) {
;             const bool last = (t == nt - 2);
;             const char* a1 = cA + (size_t)(t + 1) * kstepA;
;             const char* a2 = last ? nA : cA + (size_t)(t + 2) * kstepA; const char* b2 = last ? nB : cB + (size_t)(t + 2) * kstepB;
;             const char* a3 = a2 + kstepA; const char* b3 = b2 + kstepB;
;             PG8_LDB(B0, 0, 0); PG8_SCHED; PG8_LDA(At, 0, 0); PG8_STAGE(PG8_SA(1, 1), a1 + hstep, voffA);
;             PG8_WAIT_L(8); PG8_BAR; PG8_WAIT_L(0); PG8_MMA(0, 0, At, B0); PG8_BAR; PG8_SCHED;
;             PG8_LDB(B1, 0, 1); PG8_STAGE(PG8_SB(0, 0), b2, voffB);
;             PG8_BAR; PG8_WAIT_L(0); PG8_MMA(0, 1, At, B1); PG8_BAR;
;             PG8_LDA(At, 0, 1); PG8_STAGE(PG8_SA(0, 0), a2, voffA);
;             PG8_BAR; PG8_WAIT_L(0); PG8_MMA(1, 0, At, B0); PG8_BAR; PG8_SCHED;
;             PG8_STAGE(PG8_SB(0, 1), b2 + hstep, voffB);
.LBB0_438:
	s_ashr_i32 s13, s12, 31
	v_cmp_lt_i64_e32 vcc, s[14:15], v[140:141]
	s_lshl_b64 s[14:15], s[12:13], 15
	s_add_u32 s14, s2, s14
	s_addc_u32 s15, s3, s15
	s_and_b64 s[16:17], vcc, exec
	s_cselect_b32 s13, s15, s25
	s_cselect_b32 s55, s14, s24
	s_ashr_i32 s11, s10, 31
	s_lshl_b64 s[16:17], s[10:11], 15
	s_add_u32 s16, s34, s16
	s_addc_u32 s17, s35, s17
	s_and_b64 s[26:27], vcc, exec
	s_cselect_b32 s11, s17, s21
	s_cselect_b32 s60, s16, s20
	s_add_u32 s61, s20, 0x80000
	s_addc_u32 s63, s21, 0
	s_add_u32 s20, s24, 0x404000
	v_mov_b32_e32 v0, 0
	s_addc_u32 s21, s25, 0
	s_mov_b32 s68, -2
	ds_read_b128 v[154:157], v150
	ds_read_b128 v[158:161], v150 offset:1024
	ds_read_b128 v[162:165], v150 offset:2048
	ds_read_b128 v[166:169], v150 offset:3072
	s_add_u32 s24, s20, 0x3fc000
	s_addc_u32 s25, s21, 0
	s_cmpk_eq_i32 s68, 0x54
	s_cselect_b32 s28, s55, s24
	s_cselect_b32 s29, s13, s25
	s_cselect_b32 s25, s11, s63
	s_cselect_b32 s24, s60, s61
	s_add_u32 s26, s28, 0x400000
	s_addc_u32 s27, s29, 0
	v_lshl_add_u64 v[144:145], s[20:21], 0, v[136:137]
	s_add_i32 m0, s19, 0xc000
	ds_read_b128 v[170:173], v151
	ds_read_b128 v[174:177], v151 offset:1024
	ds_read_b128 v[186:189], v151 offset:2048
	ds_read_b128 v[190:193], v151 offset:3072
	ds_read_b128 v[194:197], v151 offset:4096
	ds_read_b128 v[198:201], v151 offset:5120
	ds_read_b128 v[202:205], v151 offset:6144
	ds_read_b128 v[206:209], v151 offset:7168
	global_load_lds_dwordx4 v[144:145], off
	v_lshl_add_u64 v[144:145], s[20:21], 0, v[138:139]
	s_add_i32 m0, s19, 0xe000
	s_nop 0
	global_load_lds_dwordx4 v[144:145], off
	ds_read_b128 v[210:213], v152
	ds_read_b128 v[214:217], v152 offset:1024
	ds_read_b128 v[218:221], v152 offset:2048
	ds_read_b128 v[222:225], v152 offset:3072
	s_waitcnt lgkmcnt(0)
	s_waitcnt vmcnt(8)
	s_barrier
	s_nop 0
	v_mfma_f32_16x16x32_bf16 v[124:127], v[154:157], v[170:173], 0
	v_mfma_f32_16x16x32_bf16 v[120:123], v[162:165], v[170:173], 0
	v_mfma_f32_16x16x32_bf16 v[112:115], v[154:157], v[186:189], 0
	v_mfma_f32_16x16x32_bf16 v[104:107], v[162:165], v[186:189], 0
	v_mfma_f32_16x16x32_bf16 v[96:99], v[154:157], v[194:197], 0
	v_mfma_f32_16x16x32_bf16 v[88:91], v[162:165], v[194:197], 0
	v_mfma_f32_16x16x32_bf16 v[80:83], v[154:157], v[202:205], 0
	v_mfma_f32_16x16x32_bf16 v[72:75], v[162:165], v[202:205], 0
	v_mfma_f32_16x16x32_bf16 v[124:127], v[158:161], v[174:177], v[124:127]
	v_mfma_f32_16x16x32_bf16 v[120:123], v[166:169], v[174:177], v[120:123]
	v_mfma_f32_16x16x32_bf16 v[112:115], v[158:161], v[190:193], v[112:115]
	v_mfma_f32_16x16x32_bf16 v[104:107], v[166:169], v[190:193], v[104:107]
	v_mfma_f32_16x16x32_bf16 v[96:99], v[158:161], v[198:201], v[96:99]
	v_mfma_f32_16x16x32_bf16 v[88:91], v[166:169], v[198:201], v[88:91]
	v_mfma_f32_16x16x32_bf16 v[80:83], v[158:161], v[206:209], v[80:83]
	v_mfma_f32_16x16x32_bf16 v[72:75], v[166:169], v[206:209], v[72:75]
	v_mfma_f32_16x16x32_bf16 v[116:119], v[210:213], v[170:173], 0
	v_mfma_f32_16x16x32_bf16 v[108:111], v[218:221], v[170:173], 0
	v_mfma_f32_16x16x32_bf16 v[100:103], v[210:213], v[186:189], 0
	v_mfma_f32_16x16x32_bf16 v[92:95], v[218:221], v[186:189], 0
	v_mfma_f32_16x16x32_bf16 v[84:87], v[210:213], v[194:197], 0
	v_mfma_f32_16x16x32_bf16 v[76:79], v[218:221], v[194:197], 0
	v_mfma_f32_16x16x32_bf16 v[68:71], v[210:213], v[202:205], 0
	v_mfma_f32_16x16x32_bf16 v[64:67], v[218:221], v[202:205], 0
	v_mfma_f32_16x16x32_bf16 v[116:119], v[214:217], v[174:177], v[116:119]
	v_mfma_f32_16x16x32_bf16 v[108:111], v[222:225], v[174:177], v[108:111]
	v_mfma_f32_16x16x32_bf16 v[100:103], v[214:217], v[190:193], v[100:103]
	v_mfma_f32_16x16x32_bf16 v[92:95], v[222:225], v[190:193], v[92:95]
	v_mfma_f32_16x16x32_bf16 v[84:87], v[214:217], v[198:201], v[84:87]
	v_mfma_f32_16x16x32_bf16 v[76:79], v[222:225], v[198:201], v[76:79]
	v_mfma_f32_16x16x32_bf16 v[68:71], v[214:217], v[206:209], v[68:71]
	v_mfma_f32_16x16x32_bf16 v[64:67], v[222:225], v[206:209], v[64:67]
	s_nop 0
	s_barrier
	s_add_i32 s69, s45, s36
	v_lshl_add_u64 v[144:145], s[24:25], 0, v[130:131]
	s_mov_b32 m0, s69
	s_nop 0
	global_load_lds_dwordx4 v[144:145], off
	v_lshl_add_u64 v[144:145], s[24:25], 0, v[134:135]
	s_add_i32 m0, s69, 0x2000
	s_nop 0
	global_load_lds_dwordx4 v[144:145], off
	s_mov_b32 m0, s19
	v_lshl_add_u64 v[144:145], s[28:29], 0, v[128:129]
	ds_read_b128 v[170:173], v151 offset:16384
	ds_read_b128 v[174:177], v151 offset:17408
	ds_read_b128 v[186:189], v151 offset:18432
	ds_read_b128 v[190:193], v151 offset:19456
	ds_read_b128 v[194:197], v151 offset:20480
	ds_read_b128 v[198:201], v151 offset:21504
	ds_read_b128 v[202:205], v151 offset:22528
	ds_read_b128 v[206:209], v151 offset:23552
	global_load_lds_dwordx4 v[144:145], off
	v_lshl_add_u64 v[144:145], s[28:29], 0, v[132:133]
	s_mov_b32 m0, s37
	s_nop 0
	global_load_lds_dwordx4 v[144:145], off
	s_add_u32 s72, s24, 0x4000
	s_addc_u32 s73, s25, 0
	s_add_i32 s69, s48, s36
	v_lshl_add_u64 v[144:145], s[72:73], 0, v[130:131]
	s_mov_b32 m0, s69
	s_nop 0
	global_load_lds_dwordx4 v[144:145], off
	v_lshl_add_u64 v[144:145], s[72:73], 0, v[134:135]
	s_add_i32 m0, s69, 0x2000
	s_nop 0
	global_load_lds_dwordx4 v[144:145], off
	s_waitcnt lgkmcnt(0)
	s_waitcnt vmcnt(8)
	s_barrier
; #define PG8_STAGE(bufoff, gbase, voff) do { _Pragma("unroll") for (int _i = 0; _i < 2; ++_i) \
;         __builtin_amdgcn_global_load_lds((const unsigned*)((const char*)(gbase) + (voff)[_i]), (LAS unsigned*)(lds + (bufoff) + ldsw + _i * 8192), 16, 0, 0); } while (0)
; #define PG8_LDA(dst, b, h) do { _Pragma("unroll") for (int m = 0; m < 4; ++m) _Pragma("unroll") for (int k = 0; k < 2; ++k) dst[m][k] = *(const LAS bf16x8*)(lds + PG8_SA(b, h) + aoff + m * 2048 + k * 1024); } while (0)
; #define PG8_LDB(dst, b, h) do { _Pragma("unroll") for (int n = 0; n < 2; ++n) _Pragma("unroll") for (int k = 0; k < 2; ++k) dst[n][k] = *(const LAS bf16x8*)(lds + PG8_SB(b, h) + boff + n * 2048 + k * 1024); } while (0)
; #define PG8_MMA(ai, bj, At, Bt) do { __builtin_amdgcn_s_setprio(1); _Pragma("unroll") for (int m = 0; m < 4; ++m) _Pragma("unroll") for (int n = 0; n < 2; ++n) _Pragma("unroll") for (int k = 0; k < 2; ++k) \
;         acc[ai][bj][m][n] = __builtin_amdgcn_mfma_f32_16x16x32_bf16(Bt[n][k], At[m][k], acc[ai][bj][m][n], 0, 0, 0); __builtin_amdgcn_s_setprio(0); } while (0)
; #define PG8_WAIT_V(n) asm volatile("s_waitcnt vmcnt(" #n ")" ::: "memory")
; #define PG8_WAIT_L(n) asm volatile("s_waitcnt lgkmcnt(" #n ")" ::: "memory")
; #define PG8_BAR __builtin_amdgcn_s_barrier()
; #define PG8_SCHED __builtin_amdgcn_sched_barrier(0)
; template <class Epi>
; __device__ __forceinline__ void gemm_phase(LAS unsigned char* lds, const Gemm g, const StaticOrder& S, const Epi& E) {
;     ...
;             PG8_BAR; PG8_WAIT_L(0); PG8_MMA(1, 0, At, B0); PG8_BAR; PG8_SCHED;
;             PG8_STAGE(PG8_SB(0, 1), b2 + hstep, voffB);
;             PG8_WAIT_V(6); PG8_BAR; PG8_MMA(1, 1, At, B1); PG8_BAR;
;             PG8_LDB(B0, 1, 0); PG8_SCHED; PG8_LDA(At, 1, 0); PG8_STAGE(PG8_SA(0, 1), a2 + hstep, voffA);
;             PG8_WAIT_L(8); PG8_BAR; PG8_WAIT_L(0); PG8_MMA(0, 0, At, B0); PG8_BAR; PG8_SCHED;
;             PG8_LDB(B1, 1, 1); PG8_STAGE(PG8_SB(1, 0), b3, voffB);
;             PG8_BAR; PG8_WAIT_L(0); PG8_MMA(0, 1, At, B1); PG8_BAR;
	s_nop 0
	v_mfma_f32_16x16x32_bf16 v[60:63], v[154:157], v[170:173], 0
	v_mfma_f32_16x16x32_bf16 v[56:59], v[162:165], v[170:173], 0
	v_mfma_f32_16x16x32_bf16 v[52:55], v[154:157], v[186:189], 0
	v_mfma_f32_16x16x32_bf16 v[44:47], v[162:165], v[186:189], 0
	v_mfma_f32_16x16x32_bf16 v[36:39], v[154:157], v[194:197], 0
	v_mfma_f32_16x16x32_bf16 v[28:31], v[162:165], v[194:197], 0
	v_mfma_f32_16x16x32_bf16 v[20:23], v[154:157], v[202:205], 0
	v_mfma_f32_16x16x32_bf16 v[12:15], v[162:165], v[202:205], 0
	v_mfma_f32_16x16x32_bf16 v[60:63], v[158:161], v[174:177], v[60:63]
	v_mfma_f32_16x16x32_bf16 v[56:59], v[166:169], v[174:177], v[56:59]
	v_mfma_f32_16x16x32_bf16 v[52:55], v[158:161], v[190:193], v[52:55]
	v_mfma_f32_16x16x32_bf16 v[44:47], v[166:169], v[190:193], v[44:47]
	v_mfma_f32_16x16x32_bf16 v[36:39], v[158:161], v[198:201], v[36:39]
	v_mfma_f32_16x16x32_bf16 v[28:31], v[166:169], v[198:201], v[28:31]
	v_mfma_f32_16x16x32_bf16 v[20:23], v[158:161], v[206:209], v[20:23]
	v_mfma_f32_16x16x32_bf16 v[12:15], v[166:169], v[206:209], v[12:15]
	v_mfma_f32_16x16x32_bf16 v[48:51], v[210:213], v[170:173], 0
	v_mfma_f32_16x16x32_bf16 v[40:43], v[218:221], v[170:173], 0
	v_mfma_f32_16x16x32_bf16 v[32:35], v[210:213], v[186:189], 0
	v_mfma_f32_16x16x32_bf16 v[24:27], v[218:221], v[186:189], 0
	v_mfma_f32_16x16x32_bf16 v[16:19], v[210:213], v[194:197], 0
	v_mfma_f32_16x16x32_bf16 v[8:11], v[218:221], v[194:197], 0
	v_mfma_f32_16x16x32_bf16 v[4:7], v[210:213], v[202:205], 0
	v_mfma_f32_16x16x32_bf16 v[0:3], v[218:221], v[202:205], 0
	v_mfma_f32_16x16x32_bf16 v[48:51], v[214:217], v[174:177], v[48:51]
	v_mfma_f32_16x16x32_bf16 v[40:43], v[222:225], v[174:177], v[40:43]
	v_mfma_f32_16x16x32_bf16 v[32:35], v[214:217], v[190:193], v[32:35]
	v_mfma_f32_16x16x32_bf16 v[24:27], v[222:225], v[190:193], v[24:27]
	v_mfma_f32_16x16x32_bf16 v[16:19], v[214:217], v[198:201], v[16:19]
	v_mfma_f32_16x16x32_bf16 v[8:11], v[222:225], v[198:201], v[8:11]
	v_mfma_f32_16x16x32_bf16 v[4:7], v[214:217], v[206:209], v[4:7]
	v_mfma_f32_16x16x32_bf16 v[0:3], v[222:225], v[206:209], v[0:3]
	s_nop 0
	s_add_i32 s69, 0, 0x18000
	v_add_u32_e32 v144, s69, v148
	s_barrier
	ds_read_b128 v[154:157], v144
	ds_read_b128 v[158:161], v144 offset:1024
	ds_read_b128 v[162:165], v144 offset:2048
	ds_read_b128 v[166:169], v144 offset:3072
	s_add_u32 s28, s28, 0x4000
	s_addc_u32 s29, s29, 0
	s_mov_b32 m0, s38
	v_lshl_add_u64 v[144:145], s[28:29], 0, v[128:129]
	ds_read_b128 v[170:173], v151 offset:32768
	ds_read_b128 v[174:177], v151 offset:33792
	ds_read_b128 v[186:189], v151 offset:34816
	ds_read_b128 v[190:193], v151 offset:35840
	ds_read_b128 v[194:197], v151 offset:36864
	ds_read_b128 v[198:201], v151 offset:37888
	ds_read_b128 v[202:205], v151 offset:38912
	ds_read_b128 v[206:209], v151 offset:39936
	global_load_lds_dwordx4 v[144:145], off
	v_lshl_add_u64 v[144:145], s[28:29], 0, v[132:133]
	s_mov_b32 m0, s39
	s_nop 0
	global_load_lds_dwordx4 v[144:145], off
	v_add_u32_e32 v253, 0x1c000, v148
	ds_read_b128 v[210:213], v253
	ds_read_b128 v[214:217], v253 offset:1024
	ds_read_b128 v[218:221], v253 offset:2048
	ds_read_b128 v[222:225], v253 offset:3072
	s_waitcnt lgkmcnt(0)
	s_waitcnt vmcnt(8)
	s_barrier
	s_nop 0
	v_mfma_f32_16x16x32_bf16 v[124:127], v[154:157], v[170:173], v[124:127]
	v_mfma_f32_16x16x32_bf16 v[120:123], v[162:165], v[170:173], v[120:123]
	v_mfma_f32_16x16x32_bf16 v[112:115], v[154:157], v[186:189], v[112:115]
	v_mfma_f32_16x16x32_bf16 v[104:107], v[162:165], v[186:189], v[104:107]
	v_mfma_f32_16x16x32_bf16 v[96:99], v[154:157], v[194:197], v[96:99]
	v_mfma_f32_16x16x32_bf16 v[88:91], v[162:165], v[194:197], v[88:91]
	v_mfma_f32_16x16x32_bf16 v[80:83], v[154:157], v[202:205], v[80:83]
	v_mfma_f32_16x16x32_bf16 v[72:75], v[162:165], v[202:205], v[72:75]
	v_mfma_f32_16x16x32_bf16 v[124:127], v[158:161], v[174:177], v[124:127]
	v_mfma_f32_16x16x32_bf16 v[120:123], v[166:169], v[174:177], v[120:123]
	v_mfma_f32_16x16x32_bf16 v[112:115], v[158:161], v[190:193], v[112:115]
	v_mfma_f32_16x16x32_bf16 v[104:107], v[166:169], v[190:193], v[104:107]
	v_mfma_f32_16x16x32_bf16 v[96:99], v[158:161], v[198:201], v[96:99]
	v_mfma_f32_16x16x32_bf16 v[88:91], v[166:169], v[198:201], v[88:91]
	v_mfma_f32_16x16x32_bf16 v[80:83], v[158:161], v[206:209], v[80:83]
	v_mfma_f32_16x16x32_bf16 v[72:75], v[166:169], v[206:209], v[72:75]
	v_mfma_f32_16x16x32_bf16 v[116:119], v[210:213], v[170:173], v[116:119]
	v_mfma_f32_16x16x32_bf16 v[108:111], v[218:221], v[170:173], v[108:111]
	v_mfma_f32_16x16x32_bf16 v[100:103], v[210:213], v[186:189], v[100:103]
	v_mfma_f32_16x16x32_bf16 v[92:95], v[218:221], v[186:189], v[92:95]
	v_mfma_f32_16x16x32_bf16 v[84:87], v[210:213], v[194:197], v[84:87]
	v_mfma_f32_16x16x32_bf16 v[76:79], v[218:221], v[194:197], v[76:79]
	v_mfma_f32_16x16x32_bf16 v[68:71], v[210:213], v[202:205], v[68:71]
	v_mfma_f32_16x16x32_bf16 v[64:67], v[218:221], v[202:205], v[64:67]
	v_mfma_f32_16x16x32_bf16 v[116:119], v[214:217], v[174:177], v[116:119]
	v_mfma_f32_16x16x32_bf16 v[108:111], v[222:225], v[174:177], v[108:111]
	v_mfma_f32_16x16x32_bf16 v[100:103], v[214:217], v[190:193], v[100:103]
	v_mfma_f32_16x16x32_bf16 v[92:95], v[222:225], v[190:193], v[92:95]
	v_mfma_f32_16x16x32_bf16 v[84:87], v[214:217], v[198:201], v[84:87]
	v_mfma_f32_16x16x32_bf16 v[76:79], v[222:225], v[198:201], v[76:79]
	v_mfma_f32_16x16x32_bf16 v[68:71], v[214:217], v[206:209], v[68:71]
	v_mfma_f32_16x16x32_bf16 v[64:67], v[222:225], v[206:209], v[64:67]
	s_nop 0
	s_barrier
; #define PG8_STAGE(bufoff, gbase, voff) do { _Pragma("unroll") for (int _i = 0; _i < 2; ++_i) \
;         __builtin_amdgcn_global_load_lds((const unsigned*)((const char*)(gbase) + (voff)[_i]), (LAS unsigned*)(lds + (bufoff) + ldsw + _i * 8192), 16, 0, 0); } while (0)
; #define PG8_LDA(dst, b, h) do { _Pragma("unroll") for (int m = 0; m < 4; ++m) _Pragma("unroll") for (int k = 0; k < 2; ++k) dst[m][k] = *(const LAS bf16x8*)(lds + PG8_SA(b, h) + aoff + m * 2048 + k * 1024); } while (0)
; #define PG8_MMA(ai, bj, At, Bt) do { __builtin_amdgcn_s_setprio(1); _Pragma("unroll") for (int m = 0; m < 4; ++m) _Pragma("unroll") for (int n = 0; n < 2; ++n) _Pragma("unroll") for (int k = 0; k < 2; ++k) \
;         acc[ai][bj][m][n] = __builtin_amdgcn_mfma_f32_16x16x32_bf16(Bt[n][k], At[m][k], acc[ai][bj][m][n], 0, 0, 0); __builtin_amdgcn_s_setprio(0); } while (0)
; #define PG8_WAIT_V(n) asm volatile("s_waitcnt vmcnt(" #n ")" ::: "memory")
; #define PG8_WAIT_L(n) asm volatile("s_waitcnt lgkmcnt(" #n ")" ::: "memory")
; #define PG8_BAR __builtin_amdgcn_s_barrier()
; #define PG8_SCHED __builtin_amdgcn_sched_barrier(0)
; template <class Epi>
; __device__ __forceinline__ void gemm_phase(LAS unsigned char* lds, const Gemm g, const StaticOrder& S, const Epi& E) {
;     ...
;             PG8_LDA(At, 1, 1); PG8_STAGE(PG8_SA(1, 0), a3, voffA);
;             PG8_BAR; PG8_WAIT_L(0); PG8_MMA(1, 0, At, B0); PG8_BAR; PG8_SCHED;
;             PG8_STAGE(PG8_SB(1, 1), b3 + hstep, voffB);
;             PG8_WAIT_V(6); PG8_BAR; PG8_MMA(1, 1, At, B1); PG8_BAR;
	s_add_i32 s72, 0, 0x1c000
	s_add_u32 s28, s24, 0x40000
	v_add_u32_e32 v144, s72, v148
	s_addc_u32 s29, s25, 0
	s_add_i32 s69, s69, s36
	s_nop 0
	v_lshl_add_u64 v[144:145], s[28:29], 0, v[130:131]
	s_mov_b32 m0, s69
	s_nop 0
	global_load_lds_dwordx4 v[144:145], off
	v_lshl_add_u64 v[144:145], s[28:29], 0, v[134:135]
	s_add_i32 m0, s69, 0x2000
	s_nop 0
	global_load_lds_dwordx4 v[144:145], off
	s_mov_b32 m0, s41
	v_lshl_add_u64 v[144:145], s[26:27], 0, v[128:129]
	ds_read_b128 v[170:173], v151 offset:49152
	ds_read_b128 v[174:177], v151 offset:50176
	ds_read_b128 v[186:189], v151 offset:51200
	ds_read_b128 v[190:193], v151 offset:52224
	ds_read_b128 v[194:197], v151 offset:53248
	ds_read_b128 v[198:201], v151 offset:54272
	ds_read_b128 v[202:205], v151 offset:55296
	ds_read_b128 v[206:209], v151 offset:56320
	global_load_lds_dwordx4 v[144:145], off
	v_lshl_add_u64 v[144:145], s[26:27], 0, v[132:133]
	s_mov_b32 m0, s42
	s_nop 0
	global_load_lds_dwordx4 v[144:145], off
	s_add_u32 s24, s24, 0x44000
	s_addc_u32 s25, s25, 0
	s_add_i32 s26, s72, s36
	v_lshl_add_u64 v[144:145], s[24:25], 0, v[130:131]
	s_mov_b32 m0, s26
	s_nop 0
	global_load_lds_dwordx4 v[144:145], off
	v_lshl_add_u64 v[144:145], s[24:25], 0, v[134:135]
	s_add_i32 m0, s26, 0x2000
	s_nop 0
	global_load_lds_dwordx4 v[144:145], off
	s_waitcnt lgkmcnt(0)
	s_waitcnt vmcnt(8)
	s_barrier
	s_nop 0
	v_mfma_f32_16x16x32_bf16 v[60:63], v[154:157], v[170:173], v[60:63]
	v_mfma_f32_16x16x32_bf16 v[56:59], v[162:165], v[170:173], v[56:59]
	v_mfma_f32_16x16x32_bf16 v[52:55], v[154:157], v[186:189], v[52:55]
	v_mfma_f32_16x16x32_bf16 v[44:47], v[162:165], v[186:189], v[44:47]
	v_mfma_f32_16x16x32_bf16 v[36:39], v[154:157], v[194:197], v[36:39]
	v_mfma_f32_16x16x32_bf16 v[28:31], v[162:165], v[194:197], v[28:31]
	v_mfma_f32_16x16x32_bf16 v[20:23], v[154:157], v[202:205], v[20:23]
	v_mfma_f32_16x16x32_bf16 v[12:15], v[162:165], v[202:205], v[12:15]
	v_mfma_f32_16x16x32_bf16 v[60:63], v[158:161], v[174:177], v[60:63]
	v_mfma_f32_16x16x32_bf16 v[56:59], v[166:169], v[174:177], v[56:59]
	v_mfma_f32_16x16x32_bf16 v[52:55], v[158:161], v[190:193], v[52:55]
	v_mfma_f32_16x16x32_bf16 v[44:47], v[166:169], v[190:193], v[44:47]
	v_mfma_f32_16x16x32_bf16 v[36:39], v[158:161], v[198:201], v[36:39]
	v_mfma_f32_16x16x32_bf16 v[28:31], v[166:169], v[198:201], v[28:31]
	v_mfma_f32_16x16x32_bf16 v[20:23], v[158:161], v[206:209], v[20:23]
	v_mfma_f32_16x16x32_bf16 v[12:15], v[166:169], v[206:209], v[12:15]
	v_mfma_f32_16x16x32_bf16 v[48:51], v[210:213], v[170:173], v[48:51]
	v_mfma_f32_16x16x32_bf16 v[40:43], v[218:221], v[170:173], v[40:43]
	v_mfma_f32_16x16x32_bf16 v[32:35], v[210:213], v[186:189], v[32:35]
	v_mfma_f32_16x16x32_bf16 v[24:27], v[218:221], v[186:189], v[24:27]
	v_mfma_f32_16x16x32_bf16 v[16:19], v[210:213], v[194:197], v[16:19]
	v_mfma_f32_16x16x32_bf16 v[8:11], v[218:221], v[194:197], v[8:11]
	v_mfma_f32_16x16x32_bf16 v[4:7], v[210:213], v[202:205], v[4:7]
	v_mfma_f32_16x16x32_bf16 v[0:3], v[218:221], v[202:205], v[0:3]
	v_mfma_f32_16x16x32_bf16 v[48:51], v[214:217], v[174:177], v[48:51]
	v_mfma_f32_16x16x32_bf16 v[40:43], v[222:225], v[174:177], v[40:43]
	v_mfma_f32_16x16x32_bf16 v[32:35], v[214:217], v[190:193], v[32:35]
	v_mfma_f32_16x16x32_bf16 v[24:27], v[222:225], v[190:193], v[24:27]
	v_mfma_f32_16x16x32_bf16 v[16:19], v[214:217], v[198:201], v[16:19]
	v_mfma_f32_16x16x32_bf16 v[8:11], v[222:225], v[198:201], v[8:11]
	v_mfma_f32_16x16x32_bf16 v[4:7], v[214:217], v[206:209], v[4:7]
	v_mfma_f32_16x16x32_bf16 v[0:3], v[222:225], v[206:209], v[0:3]
	s_nop 0
	s_add_i32 s68, s68, 2
	s_add_u32 s61, s61, 0x80000
	s_addc_u32 s63, s63, 0
	s_add_u32 s20, s20, 0x800000
	s_addc_u32 s21, s21, 0
	s_cmpk_gt_u32 s68, 0x55
	s_barrier

; #define PG8_STAGE(bufoff, gbase, voff) do { _Pragma("unroll") for (int _i = 0; _i < 2; ++_i) \
;         __builtin_amdgcn_global_load_lds((const unsigned*)((const char*)(gbase) + (voff)[_i]), (LAS unsigned*)(lds + (bufoff) + ldsw + _i * 8192), 16, 0, 0); } while (0)
; #define PG8_LDA(dst, b, h) do { _Pragma("unroll") for (int m = 0; m < 4; ++m) _Pragma("unroll") for (int k = 0; k < 2; ++k) dst[m][k] = *(const LAS bf16x8*)(lds + PG8_SA(b, h) + aoff + m * 2048 + k * 1024); } while (0)
; #define PG8_LDB(dst, b, h) do { _Pragma("unroll") for (int n = 0; n < 2; ++n) _Pragma("unroll") for (int k = 0; k < 2; ++k) dst[n][k] = *(const LAS bf16x8*)(lds + PG8_SB(b, h) + boff + n * 2048 + k * 1024); } while (0)
; #define PG8_MMA(ai, bj, At, Bt) do { __builtin_amdgcn_s_setprio(1); _Pragma("unroll") for (int m = 0; m < 4; ++m) _Pragma("unroll") for (int n = 0; n < 2; ++n) _Pragma("unroll") for (int k = 0; k < 2; ++k) \
;         acc[ai][bj][m][n] = __builtin_amdgcn_mfma_f32_16x16x32_bf16(Bt[n][k], At[m][k], acc[ai][bj][m][n], 0, 0, 0); __builtin_amdgcn_s_setprio(0); } while (0)
; template <class Epi>
; __device__ __forceinline__ void gemm_phase(LAS unsigned char* lds, const Gemm g, const StaticOrder& S, const Epi& E) {
;     ...
;         const bool has_next = S.next(ui + 1, nxt);
;         const char* nA = has_next ? (const char*)g.A + (size_t)nxt.pm * tstep : cA; const char* nB = has_next ? (const char*)g.Bt + (size_t)nxt.pn * tstep : cB;
;         for (int t = 0; t < nt; t += 2) {
;             const bool last = (t == nt - 2);
;             const char* a1 = cA + (size_t)(t + 1) * kstepA;
;             const char* a2 = last ? nA : cA + (size_t)(t + 2) * kstepA; const char* b2 = last ? nB : cB + (size_t)(t + 2) * kstepB;
;             const char* a3 = a2 + kstepA; const char* b3 = b2 + kstepB;
;             PG8_LDB(B0, 0, 0); PG8_SCHED; PG8_LDA(At, 0, 0); PG8_STAGE(PG8_SA(1, 1), a1 + hstep, voffA);
;             PG8_WAIT_L(8); PG8_BAR; PG8_WAIT_L(0); PG8_MMA(0, 0, At, B0); PG8_BAR; PG8_SCHED;
;             PG8_LDB(B1, 0, 1); PG8_STAGE(PG8_SB(0, 0), b2, voffB);
;             PG8_BAR; PG8_WAIT_L(0); PG8_MMA(0, 1, At, B1); PG8_BAR;
;             PG8_LDA(At, 0, 1); PG8_STAGE(PG8_SA(0, 0), a2, voffA);
;             PG8_BAR; PG8_WAIT_L(0); PG8_MMA(1, 0, At, B0); PG8_BAR; PG8_SCHED;
;             PG8_STAGE(PG8_SB(0, 1), b2 + hstep, voffB);
.LBB0_562:
	s_ashr_i32 s7, s6, 31
	v_cmp_lt_i64_e32 vcc, s[8:9], v[146:147]
	s_lshl_b64 s[8:9], s[6:7], 15
	s_add_u32 s8, s88, s8
	s_addc_u32 s9, s89, s9
	s_and_b64 s[10:11], vcc, exec
	s_cselect_b32 s7, s9, s19
	s_cselect_b32 s48, s8, s18
	s_ashr_i32 s1, s0, 31
	s_lshl_b64 s[10:11], s[0:1], 15
	s_add_u32 s10, s27, s10
	s_addc_u32 s11, s28, s11
	s_and_b64 s[14:15], vcc, exec
	s_cselect_b32 s15, s11, s17
	s_cselect_b32 s14, s10, s16
	s_add_u32 s16, s16, 0x140000
	s_addc_u32 s17, s17, 0
	s_add_u32 s18, s18, 0x404000
	v_mov_b32_e32 v0, 0
	s_addc_u32 s19, s19, 0
	s_mov_b32 s1, -2
	s_cmp_eq_u32 s1, 28
	s_cselect_b64 s[22:23], -1, 0
	s_and_b64 vcc, exec, s[22:23]
	s_mov_b64 s[20:21], s[14:15]
	s_cbranch_vccnz .Lpeel_body_2
	s_mov_b64 s[20:21], s[16:17]
.Lpeel_body_2:
	v_add_u32_e32 v164, s42, v133
	ds_read_b128 v[150:153], v164
	ds_read_b128 v[156:159], v164 offset:1024
	ds_read_b128 v[160:163], v164 offset:2048
	ds_read_b128 v[164:167], v164 offset:3072
	s_add_u32 s24, s18, 0x3fc000
	s_addc_u32 s25, s19, 0
	s_and_b64 s[22:23], exec, s[22:23]
	s_cselect_b32 s24, s48, s24
	s_cselect_b32 s25, s7, s25
	s_add_u32 s22, s24, 0x400000
	s_addc_u32 s23, s25, 0
	v_lshl_add_u64 v[206:207], s[18:19], 0, v[142:143]
	s_add_i32 m0, s13, 0xc000
	ds_read_b128 v[168:171], v155
	ds_read_b128 v[172:175], v155 offset:1024
	ds_read_b128 v[176:179], v155 offset:2048
	ds_read_b128 v[186:189], v155 offset:3072
	ds_read_b128 v[190:193], v155 offset:4096
	ds_read_b128 v[194:197], v155 offset:5120
	ds_read_b128 v[198:201], v155 offset:6144
	ds_read_b128 v[202:205], v155 offset:7168
	global_load_lds_dwordx4 v[206:207], off
	v_lshl_add_u64 v[206:207], s[18:19], 0, v[144:145]
	s_add_i32 m0, s13, 0xe000
	s_nop 0
	global_load_lds_dwordx4 v[206:207], off
	v_add_u32_e32 v253, 0x14000, v133
	ds_read_b128 v[206:209], v253
	ds_read_b128 v[210:213], v253 offset:1024
	ds_read_b128 v[214:217], v253 offset:2048
	ds_read_b128 v[218:221], v253 offset:3072
	s_waitcnt lgkmcnt(0)
	s_waitcnt vmcnt(8)
	s_barrier
	s_nop 0
	v_mfma_f32_16x16x32_bf16 v[124:127], v[150:153], v[168:171], 0
	v_mfma_f32_16x16x32_bf16 v[120:123], v[160:163], v[168:171], 0
	v_mfma_f32_16x16x32_bf16 v[116:119], v[150:153], v[176:179], 0
	v_mfma_f32_16x16x32_bf16 v[108:111], v[160:163], v[176:179], 0
	v_mfma_f32_16x16x32_bf16 v[100:103], v[150:153], v[190:193], 0
	v_mfma_f32_16x16x32_bf16 v[92:95], v[160:163], v[190:193], 0
	v_mfma_f32_16x16x32_bf16 v[84:87], v[150:153], v[198:201], 0
	v_mfma_f32_16x16x32_bf16 v[76:79], v[160:163], v[198:201], 0
	v_mfma_f32_16x16x32_bf16 v[124:127], v[156:159], v[172:175], v[124:127]
	v_mfma_f32_16x16x32_bf16 v[120:123], v[164:167], v[172:175], v[120:123]
	v_mfma_f32_16x16x32_bf16 v[116:119], v[156:159], v[186:189], v[116:119]
	v_mfma_f32_16x16x32_bf16 v[108:111], v[164:167], v[186:189], v[108:111]
	v_mfma_f32_16x16x32_bf16 v[100:103], v[156:159], v[194:197], v[100:103]
	v_mfma_f32_16x16x32_bf16 v[92:95], v[164:167], v[194:197], v[92:95]
	v_mfma_f32_16x16x32_bf16 v[84:87], v[156:159], v[202:205], v[84:87]
	v_mfma_f32_16x16x32_bf16 v[76:79], v[164:167], v[202:205], v[76:79]
	v_mfma_f32_16x16x32_bf16 v[112:115], v[206:209], v[168:171], 0
	v_mfma_f32_16x16x32_bf16 v[104:107], v[214:217], v[168:171], 0
	v_mfma_f32_16x16x32_bf16 v[96:99], v[206:209], v[176:179], 0
	v_mfma_f32_16x16x32_bf16 v[88:91], v[214:217], v[176:179], 0
	v_mfma_f32_16x16x32_bf16 v[80:83], v[206:209], v[190:193], 0
	v_mfma_f32_16x16x32_bf16 v[72:75], v[214:217], v[190:193], 0
	v_mfma_f32_16x16x32_bf16 v[68:71], v[206:209], v[198:201], 0
	v_mfma_f32_16x16x32_bf16 v[64:67], v[214:217], v[198:201], 0
	v_mfma_f32_16x16x32_bf16 v[112:115], v[210:213], v[172:175], v[112:115]
	v_mfma_f32_16x16x32_bf16 v[104:107], v[218:221], v[172:175], v[104:107]
	v_mfma_f32_16x16x32_bf16 v[96:99], v[210:213], v[186:189], v[96:99]
	v_mfma_f32_16x16x32_bf16 v[88:91], v[218:221], v[186:189], v[88:91]
	v_mfma_f32_16x16x32_bf16 v[80:83], v[210:213], v[194:197], v[80:83]
	v_mfma_f32_16x16x32_bf16 v[72:75], v[218:221], v[194:197], v[72:75]
	v_mfma_f32_16x16x32_bf16 v[68:71], v[210:213], v[202:205], v[68:71]
	v_mfma_f32_16x16x32_bf16 v[64:67], v[218:221], v[202:205], v[64:67]
	s_nop 0
	s_barrier
	s_add_i32 s49, s42, s29
	v_add_u32_e32 v185, s43, v133
	v_lshl_add_u64 v[222:223], s[20:21], 0, v[138:139]
	s_mov_b32 m0, s49
	s_nop 0
	global_load_lds_dwordx4 v[222:223], off
	v_lshl_add_u64 v[222:223], s[20:21], 0, v[134:135]
	s_add_i32 m0, s49, 0x2000
	s_nop 0
	global_load_lds_dwordx4 v[222:223], off
	s_mov_b32 m0, s13
	v_lshl_add_u64 v[222:223], s[24:25], 0, v[140:141]
	ds_read_b128 v[168:171], v155 offset:16384
	ds_read_b128 v[172:175], v155 offset:17408
	ds_read_b128 v[176:179], v155 offset:18432
	ds_read_b128 v[186:189], v155 offset:19456
	ds_read_b128 v[190:193], v155 offset:20480
	ds_read_b128 v[194:197], v155 offset:21504
	ds_read_b128 v[198:201], v155 offset:22528
	ds_read_b128 v[202:205], v155 offset:23552
	global_load_lds_dwordx4 v[222:223], off
	v_lshl_add_u64 v[222:223], s[24:25], 0, v[136:137]
	s_mov_b32 m0, s34
	s_nop 0
	global_load_lds_dwordx4 v[222:223], off
	s_add_u32 s50, s20, 0x4000
	s_addc_u32 s51, s21, 0
	s_add_i32 s49, s43, s29
	v_lshl_add_u64 v[254:255], s[50:51], 0, v[138:139]
	s_mov_b32 m0, s49
	s_nop 0
	global_load_lds_dwordx4 v[254:255], off
	v_lshl_add_u64 v[254:255], s[50:51], 0, v[134:135]
	s_add_i32 m0, s49, 0x2000
	s_nop 0
	global_load_lds_dwordx4 v[254:255], off
	s_waitcnt lgkmcnt(0)
	s_waitcnt vmcnt(8)
	s_barrier
; #define PG8_STAGE(bufoff, gbase, voff) do { _Pragma("unroll") for (int _i = 0; _i < 2; ++_i) \
;         __builtin_amdgcn_global_load_lds((const unsigned*)((const char*)(gbase) + (voff)[_i]), (LAS unsigned*)(lds + (bufoff) + ldsw + _i * 8192), 16, 0, 0); } while (0)
; #define PG8_LDA(dst, b, h) do { _Pragma("unroll") for (int m = 0; m < 4; ++m) _Pragma("unroll") for (int k = 0; k < 2; ++k) dst[m][k] = *(const LAS bf16x8*)(lds + PG8_SA(b, h) + aoff + m * 2048 + k * 1024); } while (0)
; #define PG8_LDB(dst, b, h) do { _Pragma("unroll") for (int n = 0; n < 2; ++n) _Pragma("unroll") for (int k = 0; k < 2; ++k) dst[n][k] = *(const LAS bf16x8*)(lds + PG8_SB(b, h) + boff + n * 2048 + k * 1024); } while (0)
; #define PG8_MMA(ai, bj, At, Bt) do { __builtin_amdgcn_s_setprio(1); _Pragma("unroll") for (int m = 0; m < 4; ++m) _Pragma("unroll") for (int n = 0; n < 2; ++n) _Pragma("unroll") for (int k = 0; k < 2; ++k) \
;         acc[ai][bj][m][n] = __builtin_amdgcn_mfma_f32_16x16x32_bf16(Bt[n][k], At[m][k], acc[ai][bj][m][n], 0, 0, 0); __builtin_amdgcn_s_setprio(0); } while (0)
; #define PG8_WAIT_V(n) asm volatile("s_waitcnt vmcnt(" #n ")" ::: "memory")
; #define PG8_WAIT_L(n) asm volatile("s_waitcnt lgkmcnt(" #n ")" ::: "memory")
; #define PG8_BAR __builtin_amdgcn_s_barrier()
; #define PG8_SCHED __builtin_amdgcn_sched_barrier(0)
; template <class Epi>
; __device__ __forceinline__ void gemm_phase(LAS unsigned char* lds, const Gemm g, const StaticOrder& S, const Epi& E) {
;     ...
;             PG8_BAR; PG8_WAIT_L(0); PG8_MMA(1, 0, At, B0); PG8_BAR; PG8_SCHED;
;             PG8_STAGE(PG8_SB(0, 1), b2 + hstep, voffB);
;             PG8_WAIT_V(6); PG8_BAR; PG8_MMA(1, 1, At, B1); PG8_BAR;
;             PG8_LDB(B0, 1, 0); PG8_SCHED; PG8_LDA(At, 1, 0); PG8_STAGE(PG8_SA(0, 1), a2 + hstep, voffA);
;             PG8_WAIT_L(8); PG8_BAR; PG8_WAIT_L(0); PG8_MMA(0, 0, At, B0); PG8_BAR; PG8_SCHED;
;             PG8_LDB(B1, 1, 1); PG8_STAGE(PG8_SB(1, 0), b3, voffB);
;             PG8_BAR; PG8_WAIT_L(0); PG8_MMA(0, 1, At, B1); PG8_BAR;
	s_nop 0
	v_mfma_f32_16x16x32_bf16 v[60:63], v[150:153], v[168:171], 0
	v_mfma_f32_16x16x32_bf16 v[56:59], v[160:163], v[168:171], 0
	v_mfma_f32_16x16x32_bf16 v[52:55], v[150:153], v[176:179], 0
	v_mfma_f32_16x16x32_bf16 v[44:47], v[160:163], v[176:179], 0
	v_mfma_f32_16x16x32_bf16 v[36:39], v[150:153], v[190:193], 0
	v_mfma_f32_16x16x32_bf16 v[28:31], v[160:163], v[190:193], 0
	v_mfma_f32_16x16x32_bf16 v[20:23], v[150:153], v[198:201], 0
	v_mfma_f32_16x16x32_bf16 v[12:15], v[160:163], v[198:201], 0
	v_mfma_f32_16x16x32_bf16 v[60:63], v[156:159], v[172:175], v[60:63]
	v_mfma_f32_16x16x32_bf16 v[56:59], v[164:167], v[172:175], v[56:59]
	v_mfma_f32_16x16x32_bf16 v[52:55], v[156:159], v[186:189], v[52:55]
	v_mfma_f32_16x16x32_bf16 v[44:47], v[164:167], v[186:189], v[44:47]
	v_mfma_f32_16x16x32_bf16 v[36:39], v[156:159], v[194:197], v[36:39]
	v_mfma_f32_16x16x32_bf16 v[28:31], v[164:167], v[194:197], v[28:31]
	v_mfma_f32_16x16x32_bf16 v[20:23], v[156:159], v[202:205], v[20:23]
	v_mfma_f32_16x16x32_bf16 v[12:15], v[164:167], v[202:205], v[12:15]
	v_mfma_f32_16x16x32_bf16 v[48:51], v[206:209], v[168:171], 0
	v_mfma_f32_16x16x32_bf16 v[40:43], v[214:217], v[168:171], 0
	v_mfma_f32_16x16x32_bf16 v[32:35], v[206:209], v[176:179], 0
	v_mfma_f32_16x16x32_bf16 v[24:27], v[214:217], v[176:179], 0
	v_mfma_f32_16x16x32_bf16 v[16:19], v[206:209], v[190:193], 0
	v_mfma_f32_16x16x32_bf16 v[8:11], v[214:217], v[190:193], 0
	v_mfma_f32_16x16x32_bf16 v[4:7], v[206:209], v[198:201], 0
	v_mfma_f32_16x16x32_bf16 v[0:3], v[214:217], v[198:201], 0
	v_mfma_f32_16x16x32_bf16 v[48:51], v[210:213], v[172:175], v[48:51]
	v_mfma_f32_16x16x32_bf16 v[40:43], v[218:221], v[172:175], v[40:43]
	v_mfma_f32_16x16x32_bf16 v[32:35], v[210:213], v[186:189], v[32:35]
	v_mfma_f32_16x16x32_bf16 v[24:27], v[218:221], v[186:189], v[24:27]
	v_mfma_f32_16x16x32_bf16 v[16:19], v[210:213], v[194:197], v[16:19]
	v_mfma_f32_16x16x32_bf16 v[8:11], v[218:221], v[194:197], v[8:11]
	v_mfma_f32_16x16x32_bf16 v[4:7], v[210:213], v[202:205], v[4:7]
	v_mfma_f32_16x16x32_bf16 v[0:3], v[218:221], v[202:205], v[0:3]
	s_nop 0
	s_add_i32 s49, 0, 0x18000
	v_add_u32_e32 v164, s49, v133
	s_barrier
	ds_read_b128 v[150:153], v164
	ds_read_b128 v[156:159], v164 offset:1024
	ds_read_b128 v[160:163], v164 offset:2048
	ds_read_b128 v[164:167], v164 offset:3072
	s_add_u32 s24, s24, 0x4000
	s_addc_u32 s25, s25, 0
	s_mov_b32 m0, s35
	v_lshl_add_u64 v[206:207], s[24:25], 0, v[140:141]
	ds_read_b128 v[168:171], v155 offset:32768
	ds_read_b128 v[172:175], v155 offset:33792
	ds_read_b128 v[176:179], v155 offset:34816
	ds_read_b128 v[186:189], v155 offset:35840
	ds_read_b128 v[190:193], v155 offset:36864
	ds_read_b128 v[194:197], v155 offset:37888
	ds_read_b128 v[198:201], v155 offset:38912
	ds_read_b128 v[202:205], v155 offset:39936
	global_load_lds_dwordx4 v[206:207], off
	v_lshl_add_u64 v[206:207], s[24:25], 0, v[136:137]
	s_mov_b32 m0, s36
	s_nop 0
	global_load_lds_dwordx4 v[206:207], off
	v_add_u32_e32 v253, 0x1c000, v133
	ds_read_b128 v[206:209], v253
	ds_read_b128 v[210:213], v253 offset:1024
	ds_read_b128 v[214:217], v253 offset:2048
	ds_read_b128 v[218:221], v253 offset:3072
	s_waitcnt lgkmcnt(0)
	s_waitcnt vmcnt(8)
	s_barrier
	s_nop 0
	v_mfma_f32_16x16x32_bf16 v[124:127], v[150:153], v[168:171], v[124:127]
	v_mfma_f32_16x16x32_bf16 v[120:123], v[160:163], v[168:171], v[120:123]
	v_mfma_f32_16x16x32_bf16 v[116:119], v[150:153], v[176:179], v[116:119]
	v_mfma_f32_16x16x32_bf16 v[108:111], v[160:163], v[176:179], v[108:111]
	v_mfma_f32_16x16x32_bf16 v[100:103], v[150:153], v[190:193], v[100:103]
	v_mfma_f32_16x16x32_bf16 v[92:95], v[160:163], v[190:193], v[92:95]
	v_mfma_f32_16x16x32_bf16 v[84:87], v[150:153], v[198:201], v[84:87]
	v_mfma_f32_16x16x32_bf16 v[76:79], v[160:163], v[198:201], v[76:79]
	v_mfma_f32_16x16x32_bf16 v[124:127], v[156:159], v[172:175], v[124:127]
	v_mfma_f32_16x16x32_bf16 v[120:123], v[164:167], v[172:175], v[120:123]
	v_mfma_f32_16x16x32_bf16 v[116:119], v[156:159], v[186:189], v[116:119]
	v_mfma_f32_16x16x32_bf16 v[108:111], v[164:167], v[186:189], v[108:111]
	v_mfma_f32_16x16x32_bf16 v[100:103], v[156:159], v[194:197], v[100:103]
	v_mfma_f32_16x16x32_bf16 v[92:95], v[164:167], v[194:197], v[92:95]
	v_mfma_f32_16x16x32_bf16 v[84:87], v[156:159], v[202:205], v[84:87]
	v_mfma_f32_16x16x32_bf16 v[76:79], v[164:167], v[202:205], v[76:79]
	v_mfma_f32_16x16x32_bf16 v[112:115], v[206:209], v[168:171], v[112:115]
	v_mfma_f32_16x16x32_bf16 v[104:107], v[214:217], v[168:171], v[104:107]
	v_mfma_f32_16x16x32_bf16 v[96:99], v[206:209], v[176:179], v[96:99]
	v_mfma_f32_16x16x32_bf16 v[88:91], v[214:217], v[176:179], v[88:91]
	v_mfma_f32_16x16x32_bf16 v[80:83], v[206:209], v[190:193], v[80:83]
	v_mfma_f32_16x16x32_bf16 v[72:75], v[214:217], v[190:193], v[72:75]
	v_mfma_f32_16x16x32_bf16 v[68:71], v[206:209], v[198:201], v[68:71]
	v_mfma_f32_16x16x32_bf16 v[64:67], v[214:217], v[198:201], v[64:67]
	v_mfma_f32_16x16x32_bf16 v[112:115], v[210:213], v[172:175], v[112:115]
	v_mfma_f32_16x16x32_bf16 v[104:107], v[218:221], v[172:175], v[104:107]
	v_mfma_f32_16x16x32_bf16 v[96:99], v[210:213], v[186:189], v[96:99]
	v_mfma_f32_16x16x32_bf16 v[88:91], v[218:221], v[186:189], v[88:91]
	v_mfma_f32_16x16x32_bf16 v[80:83], v[210:213], v[194:197], v[80:83]
	v_mfma_f32_16x16x32_bf16 v[72:75], v[218:221], v[194:197], v[72:75]
	v_mfma_f32_16x16x32_bf16 v[68:71], v[210:213], v[202:205], v[68:71]
	v_mfma_f32_16x16x32_bf16 v[64:67], v[218:221], v[202:205], v[64:67]
	s_nop 0
	s_barrier
; #define PG8_STAGE(bufoff, gbase, voff) do { _Pragma("unroll") for (int _i = 0; _i < 2; ++_i) \
;         __builtin_amdgcn_global_load_lds((const unsigned*)((const char*)(gbase) + (voff)[_i]), (LAS unsigned*)(lds + (bufoff) + ldsw + _i * 8192), 16, 0, 0); } while (0)
; #define PG8_LDA(dst, b, h) do { _Pragma("unroll") for (int m = 0; m < 4; ++m) _Pragma("unroll") for (int k = 0; k < 2; ++k) dst[m][k] = *(const LAS bf16x8*)(lds + PG8_SA(b, h) + aoff + m * 2048 + k * 1024); } while (0)
; #define PG8_MMA(ai, bj, At, Bt) do { __builtin_amdgcn_s_setprio(1); _Pragma("unroll") for (int m = 0; m < 4; ++m) _Pragma("unroll") for (int n = 0; n < 2; ++n) _Pragma("unroll") for (int k = 0; k < 2; ++k) \
;         acc[ai][bj][m][n] = __builtin_amdgcn_mfma_f32_16x16x32_bf16(Bt[n][k], At[m][k], acc[ai][bj][m][n], 0, 0, 0); __builtin_amdgcn_s_setprio(0); } while (0)
; #define PG8_WAIT_V(n) asm volatile("s_waitcnt vmcnt(" #n ")" ::: "memory")
; #define PG8_WAIT_L(n) asm volatile("s_waitcnt lgkmcnt(" #n ")" ::: "memory")
; #define PG8_BAR __builtin_amdgcn_s_barrier()
; #define PG8_SCHED __builtin_amdgcn_sched_barrier(0)
; template <class Epi>
; __device__ __forceinline__ void gemm_phase(LAS unsigned char* lds, const Gemm g, const StaticOrder& S, const Epi& E) {
;     ...
;             PG8_LDA(At, 1, 1); PG8_STAGE(PG8_SA(1, 0), a3, voffA);
;             PG8_BAR; PG8_WAIT_L(0); PG8_MMA(1, 0, At, B0); PG8_BAR; PG8_SCHED;
;             PG8_STAGE(PG8_SB(1, 1), b3 + hstep, voffB);
;             PG8_WAIT_V(6); PG8_BAR; PG8_MMA(1, 1, At, B1); PG8_BAR;
	s_add_i32 s50, 0, 0x1c000
	s_add_u32 s24, s20, 0xa0000
	s_addc_u32 s25, s21, 0
	s_add_i32 s49, s49, s29
	v_add_u32_e32 v185, s50, v133
	v_lshl_add_u64 v[222:223], s[24:25], 0, v[138:139]
	s_mov_b32 m0, s49
	s_nop 0
	global_load_lds_dwordx4 v[222:223], off
	v_lshl_add_u64 v[222:223], s[24:25], 0, v[134:135]
	s_add_i32 m0, s49, 0x2000
	s_nop 0
	global_load_lds_dwordx4 v[222:223], off
	s_mov_b32 m0, s38
	v_lshl_add_u64 v[222:223], s[22:23], 0, v[140:141]
	ds_read_b128 v[168:171], v155 offset:49152
	ds_read_b128 v[172:175], v155 offset:50176
	ds_read_b128 v[176:179], v155 offset:51200
	ds_read_b128 v[186:189], v155 offset:52224
	ds_read_b128 v[190:193], v155 offset:53248
	ds_read_b128 v[194:197], v155 offset:54272
	ds_read_b128 v[198:201], v155 offset:55296
	ds_read_b128 v[202:205], v155 offset:56320
	global_load_lds_dwordx4 v[222:223], off
	v_lshl_add_u64 v[222:223], s[22:23], 0, v[136:137]
	s_mov_b32 m0, s39
	s_nop 0
	global_load_lds_dwordx4 v[222:223], off
	s_add_u32 s20, s20, 0xa4000
	s_addc_u32 s21, s21, 0
	s_add_i32 s22, s50, s29
	v_lshl_add_u64 v[254:255], s[20:21], 0, v[138:139]
	s_mov_b32 m0, s22
	s_nop 0
	global_load_lds_dwordx4 v[254:255], off
	v_lshl_add_u64 v[254:255], s[20:21], 0, v[134:135]
	s_add_i32 m0, s22, 0x2000
	s_nop 0
	global_load_lds_dwordx4 v[254:255], off
	s_waitcnt lgkmcnt(0)
	s_waitcnt vmcnt(8)
	s_barrier
	s_nop 0
	v_mfma_f32_16x16x32_bf16 v[60:63], v[150:153], v[168:171], v[60:63]
	v_mfma_f32_16x16x32_bf16 v[56:59], v[160:163], v[168:171], v[56:59]
	v_mfma_f32_16x16x32_bf16 v[52:55], v[150:153], v[176:179], v[52:55]
	v_mfma_f32_16x16x32_bf16 v[44:47], v[160:163], v[176:179], v[44:47]
	v_mfma_f32_16x16x32_bf16 v[36:39], v[150:153], v[190:193], v[36:39]
	v_mfma_f32_16x16x32_bf16 v[28:31], v[160:163], v[190:193], v[28:31]
	v_mfma_f32_16x16x32_bf16 v[20:23], v[150:153], v[198:201], v[20:23]
	v_mfma_f32_16x16x32_bf16 v[12:15], v[160:163], v[198:201], v[12:15]
	v_mfma_f32_16x16x32_bf16 v[60:63], v[156:159], v[172:175], v[60:63]
	v_mfma_f32_16x16x32_bf16 v[56:59], v[164:167], v[172:175], v[56:59]
	v_mfma_f32_16x16x32_bf16 v[52:55], v[156:159], v[186:189], v[52:55]
	v_mfma_f32_16x16x32_bf16 v[44:47], v[164:167], v[186:189], v[44:47]
	v_mfma_f32_16x16x32_bf16 v[36:39], v[156:159], v[194:197], v[36:39]
	v_mfma_f32_16x16x32_bf16 v[28:31], v[164:167], v[194:197], v[28:31]
	v_mfma_f32_16x16x32_bf16 v[20:23], v[156:159], v[202:205], v[20:23]
	v_mfma_f32_16x16x32_bf16 v[12:15], v[164:167], v[202:205], v[12:15]
	v_mfma_f32_16x16x32_bf16 v[48:51], v[206:209], v[168:171], v[48:51]
	v_mfma_f32_16x16x32_bf16 v[40:43], v[214:217], v[168:171], v[40:43]
	v_mfma_f32_16x16x32_bf16 v[32:35], v[206:209], v[176:179], v[32:35]
	v_mfma_f32_16x16x32_bf16 v[24:27], v[214:217], v[176:179], v[24:27]
	v_mfma_f32_16x16x32_bf16 v[16:19], v[206:209], v[190:193], v[16:19]
	v_mfma_f32_16x16x32_bf16 v[8:11], v[214:217], v[190:193], v[8:11]
	v_mfma_f32_16x16x32_bf16 v[4:7], v[206:209], v[198:201], v[4:7]
	v_mfma_f32_16x16x32_bf16 v[0:3], v[214:217], v[198:201], v[0:3]
	v_mfma_f32_16x16x32_bf16 v[48:51], v[210:213], v[172:175], v[48:51]
	v_mfma_f32_16x16x32_bf16 v[40:43], v[218:221], v[172:175], v[40:43]
	v_mfma_f32_16x16x32_bf16 v[32:35], v[210:213], v[186:189], v[32:35]
	v_mfma_f32_16x16x32_bf16 v[24:27], v[218:221], v[186:189], v[24:27]
	v_mfma_f32_16x16x32_bf16 v[16:19], v[210:213], v[194:197], v[16:19]
	v_mfma_f32_16x16x32_bf16 v[8:11], v[218:221], v[194:197], v[8:11]
	v_mfma_f32_16x16x32_bf16 v[4:7], v[210:213], v[202:205], v[4:7]
	v_mfma_f32_16x16x32_bf16 v[0:3], v[218:221], v[202:205], v[0:3]
	s_nop 0
	s_add_i32 s1, s1, 2
	s_add_u32 s16, s16, 0x140000
	s_addc_u32 s17, s17, 0
	s_add_u32 s18, s18, 0x800000
	s_addc_u32 s19, s19, 0
	s_cmp_gt_u32 s1, 29
	s_barrier
	s_branch .LBB0_564

; #define PG8_STAGE(bufoff, gbase, voff) do { _Pragma("unroll") for (int _i = 0; _i < 2; ++_i) \
;         __builtin_amdgcn_global_load_lds((const unsigned*)((const char*)(gbase) + (voff)[_i]), (LAS unsigned*)(lds + (bufoff) + ldsw + _i * 8192), 16, 0, 0); } while (0)
; #define PG8_LDA(dst, b, h) do { _Pragma("unroll") for (int m = 0; m < 4; ++m) _Pragma("unroll") for (int k = 0; k < 2; ++k) dst[m][k] = *(const LAS bf16x8*)(lds + PG8_SA(b, h) + aoff + m * 2048 + k * 1024); } while (0)
; #define PG8_LDB(dst, b, h) do { _Pragma("unroll") for (int n = 0; n < 2; ++n) _Pragma("unroll") for (int k = 0; k < 2; ++k) dst[n][k] = *(const LAS bf16x8*)(lds + PG8_SB(b, h) + boff + n * 2048 + k * 1024); } while (0)
; #define PG8_MMA(ai, bj, At, Bt) do { __builtin_amdgcn_s_setprio(1); _Pragma("unroll") for (int m = 0; m < 4; ++m) _Pragma("unroll") for (int n = 0; n < 2; ++n) _Pragma("unroll") for (int k = 0; k < 2; ++k) \
;         acc[ai][bj][m][n] = __builtin_amdgcn_mfma_f32_16x16x32_bf16(Bt[n][k], At[m][k], acc[ai][bj][m][n], 0, 0, 0); __builtin_amdgcn_s_setprio(0); } while (0)
; template <class Epi>
; __device__ __forceinline__ void gemm_phase(LAS unsigned char* lds, const Gemm g, const StaticOrder& S, const Epi& E) {
;     ...
;         const bool has_next = S.next(ui + 1, nxt);
;         const char* nA = has_next ? (const char*)g.A + (size_t)nxt.pm * tstep : cA; const char* nB = has_next ? (const char*)g.Bt + (size_t)nxt.pn * tstep : cB;
;         for (int t = 0; t < nt; t += 2) {
;             const bool last = (t == nt - 2);
;             const char* a1 = cA + (size_t)(t + 1) * kstepA;
;             const char* a2 = last ? nA : cA + (size_t)(t + 2) * kstepA; const char* b2 = last ? nB : cB + (size_t)(t + 2) * kstepB;
;             const char* a3 = a2 + kstepA; const char* b3 = b2 + kstepB;
;             PG8_LDB(B0, 0, 0); PG8_SCHED; PG8_LDA(At, 0, 0); PG8_STAGE(PG8_SA(1, 1), a1 + hstep, voffA);
;             PG8_WAIT_L(8); PG8_BAR; PG8_WAIT_L(0); PG8_MMA(0, 0, At, B0); PG8_BAR; PG8_SCHED;
;             PG8_LDB(B1, 0, 1); PG8_STAGE(PG8_SB(0, 0), b2, voffB);
;             PG8_BAR; PG8_WAIT_L(0); PG8_MMA(0, 1, At, B1); PG8_BAR;
;             PG8_LDA(At, 0, 1); PG8_STAGE(PG8_SA(0, 0), a2, voffA);
;             PG8_BAR; PG8_WAIT_L(0); PG8_MMA(1, 0, At, B0); PG8_BAR; PG8_SCHED;
;             PG8_STAGE(PG8_SB(0, 1), b2 + hstep, voffB);
.LBB0_761:
	s_ashr_i32 s17, s16, 31
	v_cmp_lt_i64_e32 vcc, s[18:19], v[146:147]
	s_lshl_b64 s[18:19], s[16:17], 15
	s_add_u32 s18, s68, s18
	s_addc_u32 s19, s69, s19
	s_and_b64 s[20:21], vcc, exec
	s_cselect_b32 s17, s19, s27
	s_cselect_b32 s58, s18, s26
	s_ashr_i32 s15, s14, 31
	s_lshl_b64 s[20:21], s[14:15], 15
	s_add_u32 s20, s36, s20
	s_addc_u32 s21, s37, s21
	s_and_b64 s[28:29], vcc, exec
	s_cselect_b32 s15, s21, s25
	s_cselect_b32 s59, s20, s24
	s_add_u32 s60, s24, 0x80000
	s_addc_u32 s61, s25, 0
	s_add_u32 s24, s26, 0x404000
	v_mov_b32_e32 v0, 0
	s_addc_u32 s25, s27, 0
	s_mov_b32 s62, -2
	ds_read_b128 v[156:159], v153
	ds_read_b128 v[160:163], v153 offset:1024
	ds_read_b128 v[164:167], v153 offset:2048
	ds_read_b128 v[168:171], v153 offset:3072
	s_add_u32 s26, s24, 0x3fc000
	s_addc_u32 s27, s25, 0
	s_cmp_eq_u32 s62, 28
	s_cselect_b32 s30, s58, s26
	s_cselect_b32 s31, s17, s27
	s_cselect_b32 s27, s15, s61
	s_cselect_b32 s26, s59, s60
	s_add_u32 s28, s30, 0x400000
	s_addc_u32 s29, s31, 0
	v_lshl_add_u64 v[150:151], s[24:25], 0, v[142:143]
	s_add_i32 m0, s23, 0xc000
	ds_read_b128 v[172:175], v154
	ds_read_b128 v[176:179], v154 offset:1024
	ds_read_b128 v[184:187], v154 offset:2048
	ds_read_b128 v[188:191], v154 offset:3072
	ds_read_b128 v[192:195], v154 offset:4096
	ds_read_b128 v[196:199], v154 offset:5120
	ds_read_b128 v[200:203], v154 offset:6144
	ds_read_b128 v[204:207], v154 offset:7168
	global_load_lds_dwordx4 v[150:151], off
	v_lshl_add_u64 v[150:151], s[24:25], 0, v[144:145]
	s_add_i32 m0, s23, 0xe000
	s_nop 0
	global_load_lds_dwordx4 v[150:151], off
	ds_read_b128 v[208:211], v155
	ds_read_b128 v[212:215], v155 offset:1024
	ds_read_b128 v[216:219], v155 offset:2048
	ds_read_b128 v[220:223], v155 offset:3072
	s_waitcnt lgkmcnt(0)
	s_waitcnt vmcnt(8)
	s_barrier
	s_nop 0
	v_mfma_f32_16x16x32_bf16 v[124:127], v[156:159], v[172:175], 0
	v_mfma_f32_16x16x32_bf16 v[120:123], v[164:167], v[172:175], 0
	v_mfma_f32_16x16x32_bf16 v[112:115], v[156:159], v[184:187], 0
	v_mfma_f32_16x16x32_bf16 v[104:107], v[164:167], v[184:187], 0
	v_mfma_f32_16x16x32_bf16 v[96:99], v[156:159], v[192:195], 0
	v_mfma_f32_16x16x32_bf16 v[88:91], v[164:167], v[192:195], 0
	v_mfma_f32_16x16x32_bf16 v[80:83], v[156:159], v[200:203], 0
	v_mfma_f32_16x16x32_bf16 v[72:75], v[164:167], v[200:203], 0
	v_mfma_f32_16x16x32_bf16 v[124:127], v[160:163], v[176:179], v[124:127]
	v_mfma_f32_16x16x32_bf16 v[120:123], v[168:171], v[176:179], v[120:123]
	v_mfma_f32_16x16x32_bf16 v[112:115], v[160:163], v[188:191], v[112:115]
	v_mfma_f32_16x16x32_bf16 v[104:107], v[168:171], v[188:191], v[104:107]
	v_mfma_f32_16x16x32_bf16 v[96:99], v[160:163], v[196:199], v[96:99]
	v_mfma_f32_16x16x32_bf16 v[88:91], v[168:171], v[196:199], v[88:91]
	v_mfma_f32_16x16x32_bf16 v[80:83], v[160:163], v[204:207], v[80:83]
	v_mfma_f32_16x16x32_bf16 v[72:75], v[168:171], v[204:207], v[72:75]
	v_mfma_f32_16x16x32_bf16 v[116:119], v[208:211], v[172:175], 0
	v_mfma_f32_16x16x32_bf16 v[108:111], v[216:219], v[172:175], 0
	v_mfma_f32_16x16x32_bf16 v[100:103], v[208:211], v[184:187], 0
	v_mfma_f32_16x16x32_bf16 v[92:95], v[216:219], v[184:187], 0
	v_mfma_f32_16x16x32_bf16 v[84:87], v[208:211], v[192:195], 0
	v_mfma_f32_16x16x32_bf16 v[76:79], v[216:219], v[192:195], 0
	v_mfma_f32_16x16x32_bf16 v[68:71], v[208:211], v[200:203], 0
	v_mfma_f32_16x16x32_bf16 v[64:67], v[216:219], v[200:203], 0
	v_mfma_f32_16x16x32_bf16 v[116:119], v[212:215], v[176:179], v[116:119]
	v_mfma_f32_16x16x32_bf16 v[108:111], v[220:223], v[176:179], v[108:111]
	v_mfma_f32_16x16x32_bf16 v[100:103], v[212:215], v[188:191], v[100:103]
	v_mfma_f32_16x16x32_bf16 v[92:95], v[220:223], v[188:191], v[92:95]
	v_mfma_f32_16x16x32_bf16 v[84:87], v[212:215], v[196:199], v[84:87]
	v_mfma_f32_16x16x32_bf16 v[76:79], v[220:223], v[196:199], v[76:79]
	v_mfma_f32_16x16x32_bf16 v[68:71], v[212:215], v[204:207], v[68:71]
	v_mfma_f32_16x16x32_bf16 v[64:67], v[220:223], v[204:207], v[64:67]
	s_nop 0
	s_barrier
	s_add_i32 s63, s49, s38
	v_lshl_add_u64 v[150:151], s[26:27], 0, v[136:137]
	s_mov_b32 m0, s63
	s_nop 0
	global_load_lds_dwordx4 v[150:151], off
	v_lshl_add_u64 v[150:151], s[26:27], 0, v[140:141]
	s_add_i32 m0, s63, 0x2000
	s_nop 0
	global_load_lds_dwordx4 v[150:151], off
	s_mov_b32 m0, s23
	v_lshl_add_u64 v[150:151], s[30:31], 0, v[134:135]
	ds_read_b128 v[172:175], v154 offset:16384
	ds_read_b128 v[176:179], v154 offset:17408
	ds_read_b128 v[184:187], v154 offset:18432
	ds_read_b128 v[188:191], v154 offset:19456
	ds_read_b128 v[192:195], v154 offset:20480
	ds_read_b128 v[196:199], v154 offset:21504
	ds_read_b128 v[200:203], v154 offset:22528
	ds_read_b128 v[204:207], v154 offset:23552
	global_load_lds_dwordx4 v[150:151], off
	v_lshl_add_u64 v[150:151], s[30:31], 0, v[138:139]
	s_mov_b32 m0, s39
	s_nop 0
	global_load_lds_dwordx4 v[150:151], off
	s_add_u32 s64, s26, 0x4000
	s_addc_u32 s65, s27, 0
	s_add_i32 s63, s50, s38
	v_lshl_add_u64 v[150:151], s[64:65], 0, v[136:137]
	s_mov_b32 m0, s63
	s_nop 0
	global_load_lds_dwordx4 v[150:151], off
	v_lshl_add_u64 v[150:151], s[64:65], 0, v[140:141]
	s_add_i32 m0, s63, 0x2000
	s_nop 0
	global_load_lds_dwordx4 v[150:151], off
	s_waitcnt lgkmcnt(0)
	s_waitcnt vmcnt(8)
	s_barrier
; #define PG8_STAGE(bufoff, gbase, voff) do { _Pragma("unroll") for (int _i = 0; _i < 2; ++_i) \
;         __builtin_amdgcn_global_load_lds((const unsigned*)((const char*)(gbase) + (voff)[_i]), (LAS unsigned*)(lds + (bufoff) + ldsw + _i * 8192), 16, 0, 0); } while (0)
; #define PG8_LDA(dst, b, h) do { _Pragma("unroll") for (int m = 0; m < 4; ++m) _Pragma("unroll") for (int k = 0; k < 2; ++k) dst[m][k] = *(const LAS bf16x8*)(lds + PG8_SA(b, h) + aoff + m * 2048 + k * 1024); } while (0)
; #define PG8_LDB(dst, b, h) do { _Pragma("unroll") for (int n = 0; n < 2; ++n) _Pragma("unroll") for (int k = 0; k < 2; ++k) dst[n][k] = *(const LAS bf16x8*)(lds + PG8_SB(b, h) + boff + n * 2048 + k * 1024); } while (0)
; #define PG8_MMA(ai, bj, At, Bt) do { __builtin_amdgcn_s_setprio(1); _Pragma("unroll") for (int m = 0; m < 4; ++m) _Pragma("unroll") for (int n = 0; n < 2; ++n) _Pragma("unroll") for (int k = 0; k < 2; ++k) \
;         acc[ai][bj][m][n] = __builtin_amdgcn_mfma_f32_16x16x32_bf16(Bt[n][k], At[m][k], acc[ai][bj][m][n], 0, 0, 0); __builtin_amdgcn_s_setprio(0); } while (0)
; #define PG8_WAIT_V(n) asm volatile("s_waitcnt vmcnt(" #n ")" ::: "memory")
; #define PG8_WAIT_L(n) asm volatile("s_waitcnt lgkmcnt(" #n ")" ::: "memory")
; #define PG8_BAR __builtin_amdgcn_s_barrier()
; #define PG8_SCHED __builtin_amdgcn_sched_barrier(0)
; template <class Epi>
; __device__ __forceinline__ void gemm_phase(LAS unsigned char* lds, const Gemm g, const StaticOrder& S, const Epi& E) {
;     ...
;             PG8_BAR; PG8_WAIT_L(0); PG8_MMA(1, 0, At, B0); PG8_BAR; PG8_SCHED;
;             PG8_STAGE(PG8_SB(0, 1), b2 + hstep, voffB);
;             PG8_WAIT_V(6); PG8_BAR; PG8_MMA(1, 1, At, B1); PG8_BAR;
;             PG8_LDB(B0, 1, 0); PG8_SCHED; PG8_LDA(At, 1, 0); PG8_STAGE(PG8_SA(0, 1), a2 + hstep, voffA);
;             PG8_WAIT_L(8); PG8_BAR; PG8_WAIT_L(0); PG8_MMA(0, 0, At, B0); PG8_BAR; PG8_SCHED;
;             PG8_LDB(B1, 1, 1); PG8_STAGE(PG8_SB(1, 0), b3, voffB);
;             PG8_BAR; PG8_WAIT_L(0); PG8_MMA(0, 1, At, B1); PG8_BAR;
	s_nop 0
	v_mfma_f32_16x16x32_bf16 v[60:63], v[156:159], v[172:175], 0
	v_mfma_f32_16x16x32_bf16 v[56:59], v[164:167], v[172:175], 0
	v_mfma_f32_16x16x32_bf16 v[52:55], v[156:159], v[184:187], 0
	v_mfma_f32_16x16x32_bf16 v[44:47], v[164:167], v[184:187], 0
	v_mfma_f32_16x16x32_bf16 v[36:39], v[156:159], v[192:195], 0
	v_mfma_f32_16x16x32_bf16 v[28:31], v[164:167], v[192:195], 0
	v_mfma_f32_16x16x32_bf16 v[20:23], v[156:159], v[200:203], 0
	v_mfma_f32_16x16x32_bf16 v[12:15], v[164:167], v[200:203], 0
	v_mfma_f32_16x16x32_bf16 v[60:63], v[160:163], v[176:179], v[60:63]
	v_mfma_f32_16x16x32_bf16 v[56:59], v[168:171], v[176:179], v[56:59]
	v_mfma_f32_16x16x32_bf16 v[52:55], v[160:163], v[188:191], v[52:55]
	v_mfma_f32_16x16x32_bf16 v[44:47], v[168:171], v[188:191], v[44:47]
	v_mfma_f32_16x16x32_bf16 v[36:39], v[160:163], v[196:199], v[36:39]
	v_mfma_f32_16x16x32_bf16 v[28:31], v[168:171], v[196:199], v[28:31]
	v_mfma_f32_16x16x32_bf16 v[20:23], v[160:163], v[204:207], v[20:23]
	v_mfma_f32_16x16x32_bf16 v[12:15], v[168:171], v[204:207], v[12:15]
	v_mfma_f32_16x16x32_bf16 v[48:51], v[208:211], v[172:175], 0
	v_mfma_f32_16x16x32_bf16 v[40:43], v[216:219], v[172:175], 0
	v_mfma_f32_16x16x32_bf16 v[32:35], v[208:211], v[184:187], 0
	v_mfma_f32_16x16x32_bf16 v[24:27], v[216:219], v[184:187], 0
	v_mfma_f32_16x16x32_bf16 v[16:19], v[208:211], v[192:195], 0
	v_mfma_f32_16x16x32_bf16 v[8:11], v[216:219], v[192:195], 0
	v_mfma_f32_16x16x32_bf16 v[4:7], v[208:211], v[200:203], 0
	v_mfma_f32_16x16x32_bf16 v[0:3], v[216:219], v[200:203], 0
	v_mfma_f32_16x16x32_bf16 v[48:51], v[212:215], v[176:179], v[48:51]
	v_mfma_f32_16x16x32_bf16 v[40:43], v[220:223], v[176:179], v[40:43]
	v_mfma_f32_16x16x32_bf16 v[32:35], v[212:215], v[188:191], v[32:35]
	v_mfma_f32_16x16x32_bf16 v[24:27], v[220:223], v[188:191], v[24:27]
	v_mfma_f32_16x16x32_bf16 v[16:19], v[212:215], v[196:199], v[16:19]
	v_mfma_f32_16x16x32_bf16 v[8:11], v[220:223], v[196:199], v[8:11]
	v_mfma_f32_16x16x32_bf16 v[4:7], v[212:215], v[204:207], v[4:7]
	v_mfma_f32_16x16x32_bf16 v[0:3], v[220:223], v[204:207], v[0:3]
	s_nop 0
	s_add_i32 s63, 0, 0x18000
	v_add_u32_e32 v150, s63, v133
	s_barrier
	ds_read_b128 v[156:159], v150
	ds_read_b128 v[160:163], v150 offset:1024
	ds_read_b128 v[164:167], v150 offset:2048
	ds_read_b128 v[168:171], v150 offset:3072
	s_add_u32 s30, s30, 0x4000
	s_addc_u32 s31, s31, 0
	s_mov_b32 m0, s40
	v_lshl_add_u64 v[150:151], s[30:31], 0, v[134:135]
	ds_read_b128 v[172:175], v154 offset:32768
	ds_read_b128 v[176:179], v154 offset:33792
	ds_read_b128 v[184:187], v154 offset:34816
	ds_read_b128 v[188:191], v154 offset:35840
	ds_read_b128 v[192:195], v154 offset:36864
	ds_read_b128 v[196:199], v154 offset:37888
	ds_read_b128 v[200:203], v154 offset:38912
	ds_read_b128 v[204:207], v154 offset:39936
	global_load_lds_dwordx4 v[150:151], off
	v_lshl_add_u64 v[150:151], s[30:31], 0, v[138:139]
	s_mov_b32 m0, s41
	s_nop 0
	global_load_lds_dwordx4 v[150:151], off
	v_add_u32_e32 v253, 0x1c000, v133
	ds_read_b128 v[208:211], v253
	ds_read_b128 v[212:215], v253 offset:1024
	ds_read_b128 v[216:219], v253 offset:2048
	ds_read_b128 v[220:223], v253 offset:3072
	s_waitcnt lgkmcnt(0)
	s_waitcnt vmcnt(8)
	s_barrier
	s_nop 0
	v_mfma_f32_16x16x32_bf16 v[124:127], v[156:159], v[172:175], v[124:127]
	v_mfma_f32_16x16x32_bf16 v[120:123], v[164:167], v[172:175], v[120:123]
	v_mfma_f32_16x16x32_bf16 v[112:115], v[156:159], v[184:187], v[112:115]
	v_mfma_f32_16x16x32_bf16 v[104:107], v[164:167], v[184:187], v[104:107]
	v_mfma_f32_16x16x32_bf16 v[96:99], v[156:159], v[192:195], v[96:99]
	v_mfma_f32_16x16x32_bf16 v[88:91], v[164:167], v[192:195], v[88:91]
	v_mfma_f32_16x16x32_bf16 v[80:83], v[156:159], v[200:203], v[80:83]
	v_mfma_f32_16x16x32_bf16 v[72:75], v[164:167], v[200:203], v[72:75]
	v_mfma_f32_16x16x32_bf16 v[124:127], v[160:163], v[176:179], v[124:127]
	v_mfma_f32_16x16x32_bf16 v[120:123], v[168:171], v[176:179], v[120:123]
	v_mfma_f32_16x16x32_bf16 v[112:115], v[160:163], v[188:191], v[112:115]
	v_mfma_f32_16x16x32_bf16 v[104:107], v[168:171], v[188:191], v[104:107]
	v_mfma_f32_16x16x32_bf16 v[96:99], v[160:163], v[196:199], v[96:99]
	v_mfma_f32_16x16x32_bf16 v[88:91], v[168:171], v[196:199], v[88:91]
	v_mfma_f32_16x16x32_bf16 v[80:83], v[160:163], v[204:207], v[80:83]
	v_mfma_f32_16x16x32_bf16 v[72:75], v[168:171], v[204:207], v[72:75]
	v_mfma_f32_16x16x32_bf16 v[116:119], v[208:211], v[172:175], v[116:119]
	v_mfma_f32_16x16x32_bf16 v[108:111], v[216:219], v[172:175], v[108:111]
	v_mfma_f32_16x16x32_bf16 v[100:103], v[208:211], v[184:187], v[100:103]
	v_mfma_f32_16x16x32_bf16 v[92:95], v[216:219], v[184:187], v[92:95]
	v_mfma_f32_16x16x32_bf16 v[84:87], v[208:211], v[192:195], v[84:87]
	v_mfma_f32_16x16x32_bf16 v[76:79], v[216:219], v[192:195], v[76:79]
	v_mfma_f32_16x16x32_bf16 v[68:71], v[208:211], v[200:203], v[68:71]
	v_mfma_f32_16x16x32_bf16 v[64:67], v[216:219], v[200:203], v[64:67]
	v_mfma_f32_16x16x32_bf16 v[116:119], v[212:215], v[176:179], v[116:119]
	v_mfma_f32_16x16x32_bf16 v[108:111], v[220:223], v[176:179], v[108:111]
	v_mfma_f32_16x16x32_bf16 v[100:103], v[212:215], v[188:191], v[100:103]
	v_mfma_f32_16x16x32_bf16 v[92:95], v[220:223], v[188:191], v[92:95]
	v_mfma_f32_16x16x32_bf16 v[84:87], v[212:215], v[196:199], v[84:87]
	v_mfma_f32_16x16x32_bf16 v[76:79], v[220:223], v[196:199], v[76:79]
	v_mfma_f32_16x16x32_bf16 v[68:71], v[212:215], v[204:207], v[68:71]
	v_mfma_f32_16x16x32_bf16 v[64:67], v[220:223], v[204:207], v[64:67]
	s_nop 0
	s_barrier
; #define PG8_STAGE(bufoff, gbase, voff) do { _Pragma("unroll") for (int _i = 0; _i < 2; ++_i) \
;         __builtin_amdgcn_global_load_lds((const unsigned*)((const char*)(gbase) + (voff)[_i]), (LAS unsigned*)(lds + (bufoff) + ldsw + _i * 8192), 16, 0, 0); } while (0)
; #define PG8_LDA(dst, b, h) do { _Pragma("unroll") for (int m = 0; m < 4; ++m) _Pragma("unroll") for (int k = 0; k < 2; ++k) dst[m][k] = *(const LAS bf16x8*)(lds + PG8_SA(b, h) + aoff + m * 2048 + k * 1024); } while (0)
; #define PG8_MMA(ai, bj, At, Bt) do { __builtin_amdgcn_s_setprio(1); _Pragma("unroll") for (int m = 0; m < 4; ++m) _Pragma("unroll") for (int n = 0; n < 2; ++n) _Pragma("unroll") for (int k = 0; k < 2; ++k) \
;         acc[ai][bj][m][n] = __builtin_amdgcn_mfma_f32_16x16x32_bf16(Bt[n][k], At[m][k], acc[ai][bj][m][n], 0, 0, 0); __builtin_amdgcn_s_setprio(0); } while (0)
; #define PG8_WAIT_V(n) asm volatile("s_waitcnt vmcnt(" #n ")" ::: "memory")
; #define PG8_WAIT_L(n) asm volatile("s_waitcnt lgkmcnt(" #n ")" ::: "memory")
; #define PG8_BAR __builtin_amdgcn_s_barrier()
; #define PG8_SCHED __builtin_amdgcn_sched_barrier(0)
; template <class Epi>
; __device__ __forceinline__ void gemm_phase(LAS unsigned char* lds, const Gemm g, const StaticOrder& S, const Epi& E) {
;     ...
;             PG8_LDA(At, 1, 1); PG8_STAGE(PG8_SA(1, 0), a3, voffA);
;             PG8_BAR; PG8_WAIT_L(0); PG8_MMA(1, 0, At, B0); PG8_BAR; PG8_SCHED;
;             PG8_STAGE(PG8_SB(1, 1), b3 + hstep, voffB);
;             PG8_WAIT_V(6); PG8_BAR; PG8_MMA(1, 1, At, B1); PG8_BAR;
	s_add_i32 s64, 0, 0x1c000
	s_add_u32 s30, s26, 0x40000
	v_add_u32_e32 v150, s64, v133
	s_addc_u32 s31, s27, 0
	s_add_i32 s63, s63, s38
	s_nop 0
	v_lshl_add_u64 v[150:151], s[30:31], 0, v[136:137]
	s_mov_b32 m0, s63
	s_nop 0
	global_load_lds_dwordx4 v[150:151], off
	v_lshl_add_u64 v[150:151], s[30:31], 0, v[140:141]
	s_add_i32 m0, s63, 0x2000
	s_nop 0
	global_load_lds_dwordx4 v[150:151], off
	s_mov_b32 m0, s43
	v_lshl_add_u64 v[150:151], s[28:29], 0, v[134:135]
	ds_read_b128 v[172:175], v154 offset:49152
	ds_read_b128 v[176:179], v154 offset:50176
	ds_read_b128 v[184:187], v154 offset:51200
	ds_read_b128 v[188:191], v154 offset:52224
	ds_read_b128 v[192:195], v154 offset:53248
	ds_read_b128 v[196:199], v154 offset:54272
	ds_read_b128 v[200:203], v154 offset:55296
	ds_read_b128 v[204:207], v154 offset:56320
	global_load_lds_dwordx4 v[150:151], off
	v_lshl_add_u64 v[150:151], s[28:29], 0, v[138:139]
	s_mov_b32 m0, s44
	s_nop 0
	global_load_lds_dwordx4 v[150:151], off
	s_add_u32 s26, s26, 0x44000
	s_addc_u32 s27, s27, 0
	s_add_i32 s28, s64, s38
	v_lshl_add_u64 v[150:151], s[26:27], 0, v[136:137]
	s_mov_b32 m0, s28
	s_nop 0
	global_load_lds_dwordx4 v[150:151], off
	v_lshl_add_u64 v[150:151], s[26:27], 0, v[140:141]
	s_add_i32 m0, s28, 0x2000
	s_nop 0
	global_load_lds_dwordx4 v[150:151], off
	s_waitcnt lgkmcnt(0)
	s_waitcnt vmcnt(8)
	s_barrier
	s_nop 0
	v_mfma_f32_16x16x32_bf16 v[60:63], v[156:159], v[172:175], v[60:63]
	v_mfma_f32_16x16x32_bf16 v[56:59], v[164:167], v[172:175], v[56:59]
	v_mfma_f32_16x16x32_bf16 v[52:55], v[156:159], v[184:187], v[52:55]
	v_mfma_f32_16x16x32_bf16 v[44:47], v[164:167], v[184:187], v[44:47]
	v_mfma_f32_16x16x32_bf16 v[36:39], v[156:159], v[192:195], v[36:39]
	v_mfma_f32_16x16x32_bf16 v[28:31], v[164:167], v[192:195], v[28:31]
	v_mfma_f32_16x16x32_bf16 v[20:23], v[156:159], v[200:203], v[20:23]
	v_mfma_f32_16x16x32_bf16 v[12:15], v[164:167], v[200:203], v[12:15]
	v_mfma_f32_16x16x32_bf16 v[60:63], v[160:163], v[176:179], v[60:63]
	v_mfma_f32_16x16x32_bf16 v[56:59], v[168:171], v[176:179], v[56:59]
	v_mfma_f32_16x16x32_bf16 v[52:55], v[160:163], v[188:191], v[52:55]
	v_mfma_f32_16x16x32_bf16 v[44:47], v[168:171], v[188:191], v[44:47]
	v_mfma_f32_16x16x32_bf16 v[36:39], v[160:163], v[196:199], v[36:39]
	v_mfma_f32_16x16x32_bf16 v[28:31], v[168:171], v[196:199], v[28:31]
	v_mfma_f32_16x16x32_bf16 v[20:23], v[160:163], v[204:207], v[20:23]
	v_mfma_f32_16x16x32_bf16 v[12:15], v[168:171], v[204:207], v[12:15]
	v_mfma_f32_16x16x32_bf16 v[48:51], v[208:211], v[172:175], v[48:51]
	v_mfma_f32_16x16x32_bf16 v[40:43], v[216:219], v[172:175], v[40:43]
	v_mfma_f32_16x16x32_bf16 v[32:35], v[208:211], v[184:187], v[32:35]
	v_mfma_f32_16x16x32_bf16 v[24:27], v[216:219], v[184:187], v[24:27]
	v_mfma_f32_16x16x32_bf16 v[16:19], v[208:211], v[192:195], v[16:19]
	v_mfma_f32_16x16x32_bf16 v[8:11], v[216:219], v[192:195], v[8:11]
	v_mfma_f32_16x16x32_bf16 v[4:7], v[208:211], v[200:203], v[4:7]
	v_mfma_f32_16x16x32_bf16 v[0:3], v[216:219], v[200:203], v[0:3]
	v_mfma_f32_16x16x32_bf16 v[48:51], v[212:215], v[176:179], v[48:51]
	v_mfma_f32_16x16x32_bf16 v[40:43], v[220:223], v[176:179], v[40:43]
	v_mfma_f32_16x16x32_bf16 v[32:35], v[212:215], v[188:191], v[32:35]
	v_mfma_f32_16x16x32_bf16 v[24:27], v[220:223], v[188:191], v[24:27]
	v_mfma_f32_16x16x32_bf16 v[16:19], v[212:215], v[196:199], v[16:19]
	v_mfma_f32_16x16x32_bf16 v[8:11], v[220:223], v[196:199], v[8:11]
	v_mfma_f32_16x16x32_bf16 v[4:7], v[212:215], v[204:207], v[4:7]
	v_mfma_f32_16x16x32_bf16 v[0:3], v[220:223], v[204:207], v[0:3]
	s_nop 0
	s_add_i32 s62, s62, 2
	s_add_u32 s60, s60, 0x80000
	s_addc_u32 s61, s61, 0
	s_add_u32 s24, s24, 0x800000
	s_addc_u32 s25, s25, 0
	s_cmp_gt_u32 s62, 29
	s_barrier

; #define PG8_STAGE(bufoff, gbase, voff) do { _Pragma("unroll") for (int _i = 0; _i < 2; ++_i) \
;         __builtin_amdgcn_global_load_lds((const unsigned*)((const char*)(gbase) + (voff)[_i]), (LAS unsigned*)(lds + (bufoff) + ldsw + _i * 8192), 16, 0, 0); } while (0)
; #define PG8_LDA(dst, b, h) do { _Pragma("unroll") for (int m = 0; m < 4; ++m) _Pragma("unroll") for (int k = 0; k < 2; ++k) dst[m][k] = *(const LAS bf16x8*)(lds + PG8_SA(b, h) + aoff + m * 2048 + k * 1024); } while (0)
; #define PG8_LDB(dst, b, h) do { _Pragma("unroll") for (int n = 0; n < 2; ++n) _Pragma("unroll") for (int k = 0; k < 2; ++k) dst[n][k] = *(const LAS bf16x8*)(lds + PG8_SB(b, h) + boff + n * 2048 + k * 1024); } while (0)
; #define PG8_MMA(ai, bj, At, Bt) do { __builtin_amdgcn_s_setprio(1); _Pragma("unroll") for (int m = 0; m < 4; ++m) _Pragma("unroll") for (int n = 0; n < 2; ++n) _Pragma("unroll") for (int k = 0; k < 2; ++k) \
;         acc[ai][bj][m][n] = __builtin_amdgcn_mfma_f32_16x16x32_bf16(Bt[n][k], At[m][k], acc[ai][bj][m][n], 0, 0, 0); __builtin_amdgcn_s_setprio(0); } while (0)
; template <class Epi>
; __device__ __forceinline__ void gemm_phase(LAS unsigned char* lds, const Gemm g, const StaticOrder& S, const Epi& E) {
;     ...
;         const bool has_next = S.next(ui + 1, nxt);
;         const char* nA = has_next ? (const char*)g.A + (size_t)nxt.pm * tstep : cA; const char* nB = has_next ? (const char*)g.Bt + (size_t)nxt.pn * tstep : cB;
;         for (int t = 0; t < nt; t += 2) {
;             const bool last = (t == nt - 2);
;             const char* a1 = cA + (size_t)(t + 1) * kstepA;
;             const char* a2 = last ? nA : cA + (size_t)(t + 2) * kstepA; const char* b2 = last ? nB : cB + (size_t)(t + 2) * kstepB;
;             const char* a3 = a2 + kstepA; const char* b3 = b2 + kstepB;
;             PG8_LDB(B0, 0, 0); PG8_SCHED; PG8_LDA(At, 0, 0); PG8_STAGE(PG8_SA(1, 1), a1 + hstep, voffA);
;             PG8_WAIT_L(8); PG8_BAR; PG8_WAIT_L(0); PG8_MMA(0, 0, At, B0); PG8_BAR; PG8_SCHED;
;             PG8_LDB(B1, 0, 1); PG8_STAGE(PG8_SB(0, 0), b2, voffB);
;             PG8_BAR; PG8_WAIT_L(0); PG8_MMA(0, 1, At, B1); PG8_BAR;
;             PG8_LDA(At, 0, 1); PG8_STAGE(PG8_SA(0, 0), a2, voffA);
;             PG8_BAR; PG8_WAIT_L(0); PG8_MMA(1, 0, At, B0); PG8_BAR; PG8_SCHED;
;             PG8_STAGE(PG8_SB(0, 1), b2 + hstep, voffB);
.LBB0_884:
	s_ashr_i32 s9, s8, 31
	v_cmp_lt_i64_e32 vcc, s[10:11], v[140:141]
	s_lshl_b64 s[10:11], s[8:9], 15
	s_add_u32 s10, s88, s10
	s_addc_u32 s11, s89, s11
	s_and_b64 s[12:13], vcc, exec
	s_cselect_b32 s9, s11, s19
	s_cselect_b32 s44, s10, s18
	s_ashr_i32 s1, s0, 31
	s_lshl_b64 s[12:13], s[0:1], 15
	s_add_u32 s12, s25, s12
	s_addc_u32 s13, s26, s13
	s_and_b64 s[20:21], vcc, exec
	s_cselect_b32 s1, s13, s17
	s_cselect_b32 s45, s12, s16
	s_add_u32 s48, s16, 0x2c0000
	s_addc_u32 s49, s17, 0
	s_add_u32 s16, s18, 0x404000
	v_mov_b32_e32 v0, 0
	s_addc_u32 s17, s19, 0
	s_mov_b32 s50, -2
	ds_read_b128 v[152:155], v148
	ds_read_b128 v[156:159], v148 offset:1024
	ds_read_b128 v[160:163], v148 offset:2048
	ds_read_b128 v[164:167], v148 offset:3072
	s_add_u32 s18, s16, 0x3fc000
	s_addc_u32 s19, s17, 0
	s_cmp_eq_u32 s50, 28
	s_cselect_b32 s22, s44, s18
	s_cselect_b32 s23, s9, s19
	s_cselect_b32 s18, s45, s48
	s_cselect_b32 s19, s1, s49
	s_add_u32 s20, s22, 0x400000
	s_addc_u32 s21, s23, 0
	v_lshl_add_u64 v[144:145], s[16:17], 0, v[136:137]
	s_add_i32 m0, s30, 0xc000
	ds_read_b128 v[168:171], v149
	ds_read_b128 v[172:175], v149 offset:1024
	ds_read_b128 v[176:179], v149 offset:2048
	ds_read_b128 v[184:187], v149 offset:3072
	ds_read_b128 v[188:191], v149 offset:4096
	ds_read_b128 v[192:195], v149 offset:5120
	ds_read_b128 v[196:199], v149 offset:6144
	ds_read_b128 v[200:203], v149 offset:7168
	global_load_lds_dwordx4 v[144:145], off
	v_lshl_add_u64 v[144:145], s[16:17], 0, v[138:139]
	s_add_i32 m0, s30, 0xe000
	s_nop 0
	global_load_lds_dwordx4 v[144:145], off
	ds_read_b128 v[204:207], v150
	ds_read_b128 v[208:211], v150 offset:1024
	ds_read_b128 v[212:215], v150 offset:2048
	ds_read_b128 v[216:219], v150 offset:3072
	s_waitcnt lgkmcnt(0)
	s_waitcnt vmcnt(8)
	s_barrier
	s_nop 0
	v_mfma_f32_16x16x32_bf16 v[124:127], v[152:155], v[168:171], 0
	v_mfma_f32_16x16x32_bf16 v[120:123], v[160:163], v[168:171], 0
	v_mfma_f32_16x16x32_bf16 v[108:111], v[152:155], v[176:179], 0
	v_mfma_f32_16x16x32_bf16 v[104:107], v[160:163], v[176:179], 0
	v_mfma_f32_16x16x32_bf16 v[92:95], v[152:155], v[188:191], 0
	v_mfma_f32_16x16x32_bf16 v[88:91], v[160:163], v[188:191], 0
	v_mfma_f32_16x16x32_bf16 v[76:79], v[152:155], v[196:199], 0
	v_mfma_f32_16x16x32_bf16 v[72:75], v[160:163], v[196:199], 0
	v_mfma_f32_16x16x32_bf16 v[124:127], v[156:159], v[172:175], v[124:127]
	v_mfma_f32_16x16x32_bf16 v[120:123], v[164:167], v[172:175], v[120:123]
	v_mfma_f32_16x16x32_bf16 v[108:111], v[156:159], v[184:187], v[108:111]
	v_mfma_f32_16x16x32_bf16 v[104:107], v[164:167], v[184:187], v[104:107]
	v_mfma_f32_16x16x32_bf16 v[92:95], v[156:159], v[192:195], v[92:95]
	v_mfma_f32_16x16x32_bf16 v[88:91], v[164:167], v[192:195], v[88:91]
	v_mfma_f32_16x16x32_bf16 v[76:79], v[156:159], v[200:203], v[76:79]
	v_mfma_f32_16x16x32_bf16 v[72:75], v[164:167], v[200:203], v[72:75]
	v_mfma_f32_16x16x32_bf16 v[116:119], v[204:207], v[168:171], 0
	v_mfma_f32_16x16x32_bf16 v[112:115], v[212:215], v[168:171], 0
	v_mfma_f32_16x16x32_bf16 v[100:103], v[204:207], v[176:179], 0
	v_mfma_f32_16x16x32_bf16 v[96:99], v[212:215], v[176:179], 0
	v_mfma_f32_16x16x32_bf16 v[84:87], v[204:207], v[188:191], 0
	v_mfma_f32_16x16x32_bf16 v[80:83], v[212:215], v[188:191], 0
	v_mfma_f32_16x16x32_bf16 v[68:71], v[204:207], v[196:199], 0
	v_mfma_f32_16x16x32_bf16 v[64:67], v[212:215], v[196:199], 0
	v_mfma_f32_16x16x32_bf16 v[116:119], v[208:211], v[172:175], v[116:119]
	v_mfma_f32_16x16x32_bf16 v[112:115], v[216:219], v[172:175], v[112:115]
	v_mfma_f32_16x16x32_bf16 v[100:103], v[208:211], v[184:187], v[100:103]
	v_mfma_f32_16x16x32_bf16 v[96:99], v[216:219], v[184:187], v[96:99]
	v_mfma_f32_16x16x32_bf16 v[84:87], v[208:211], v[192:195], v[84:87]
	v_mfma_f32_16x16x32_bf16 v[80:83], v[216:219], v[192:195], v[80:83]
	v_mfma_f32_16x16x32_bf16 v[68:71], v[208:211], v[200:203], v[68:71]
	v_mfma_f32_16x16x32_bf16 v[64:67], v[216:219], v[200:203], v[64:67]
	s_nop 0
	s_barrier
	s_add_i32 s51, s42, s27
	v_lshl_add_u64 v[144:145], s[18:19], 0, v[132:133]
	s_mov_b32 m0, s51
	s_nop 0
	global_load_lds_dwordx4 v[144:145], off
	v_lshl_add_u64 v[144:145], s[18:19], 0, v[130:131]
	s_add_i32 m0, s51, 0x2000
	s_nop 0
	global_load_lds_dwordx4 v[144:145], off
	s_mov_b32 m0, s30
	v_lshl_add_u64 v[144:145], s[22:23], 0, v[132:133]
	ds_read_b128 v[168:171], v149 offset:16384
	ds_read_b128 v[172:175], v149 offset:17408
	ds_read_b128 v[176:179], v149 offset:18432
	ds_read_b128 v[184:187], v149 offset:19456
	ds_read_b128 v[188:191], v149 offset:20480
	ds_read_b128 v[192:195], v149 offset:21504
	ds_read_b128 v[196:199], v149 offset:22528
	ds_read_b128 v[200:203], v149 offset:23552
	global_load_lds_dwordx4 v[144:145], off
	v_lshl_add_u64 v[144:145], s[22:23], 0, v[130:131]
	s_mov_b32 m0, s31
	s_nop 0
	global_load_lds_dwordx4 v[144:145], off
	s_add_u32 s54, s18, 0x4000
	s_addc_u32 s55, s19, 0
	s_add_i32 s51, s43, s27
	v_lshl_add_u64 v[144:145], s[54:55], 0, v[132:133]
	s_mov_b32 m0, s51
	s_nop 0
	global_load_lds_dwordx4 v[144:145], off
	v_lshl_add_u64 v[144:145], s[54:55], 0, v[130:131]
	s_add_i32 m0, s51, 0x2000
	s_nop 0
	global_load_lds_dwordx4 v[144:145], off
	s_waitcnt lgkmcnt(0)
	s_waitcnt vmcnt(8)
	s_barrier
; #define PG8_STAGE(bufoff, gbase, voff) do { _Pragma("unroll") for (int _i = 0; _i < 2; ++_i) \
;         __builtin_amdgcn_global_load_lds((const unsigned*)((const char*)(gbase) + (voff)[_i]), (LAS unsigned*)(lds + (bufoff) + ldsw + _i * 8192), 16, 0, 0); } while (0)
; #define PG8_LDA(dst, b, h) do { _Pragma("unroll") for (int m = 0; m < 4; ++m) _Pragma("unroll") for (int k = 0; k < 2; ++k) dst[m][k] = *(const LAS bf16x8*)(lds + PG8_SA(b, h) + aoff + m * 2048 + k * 1024); } while (0)
; #define PG8_LDB(dst, b, h) do { _Pragma("unroll") for (int n = 0; n < 2; ++n) _Pragma("unroll") for (int k = 0; k < 2; ++k) dst[n][k] = *(const LAS bf16x8*)(lds + PG8_SB(b, h) + boff + n * 2048 + k * 1024); } while (0)
; #define PG8_MMA(ai, bj, At, Bt) do { __builtin_amdgcn_s_setprio(1); _Pragma("unroll") for (int m = 0; m < 4; ++m) _Pragma("unroll") for (int n = 0; n < 2; ++n) _Pragma("unroll") for (int k = 0; k < 2; ++k) \
;         acc[ai][bj][m][n] = __builtin_amdgcn_mfma_f32_16x16x32_bf16(Bt[n][k], At[m][k], acc[ai][bj][m][n], 0, 0, 0); __builtin_amdgcn_s_setprio(0); } while (0)
; #define PG8_WAIT_V(n) asm volatile("s_waitcnt vmcnt(" #n ")" ::: "memory")
; #define PG8_WAIT_L(n) asm volatile("s_waitcnt lgkmcnt(" #n ")" ::: "memory")
; #define PG8_BAR __builtin_amdgcn_s_barrier()
; #define PG8_SCHED __builtin_amdgcn_sched_barrier(0)
; template <class Epi>
; __device__ __forceinline__ void gemm_phase(LAS unsigned char* lds, const Gemm g, const StaticOrder& S, const Epi& E) {
;     ...
;             PG8_LDB(B0, 0, 0); PG8_SCHED; PG8_LDA(At, 0, 0); PG8_STAGE(PG8_SA(1, 1), a1 + hstep, voffA);
;             PG8_WAIT_L(8); PG8_BAR; PG8_WAIT_L(0); PG8_MMA(0, 0, At, B0); PG8_BAR; PG8_SCHED;
;             PG8_LDB(B1, 0, 1); PG8_STAGE(PG8_SB(0, 0), b2, voffB);
;             PG8_BAR; PG8_WAIT_L(0); PG8_MMA(0, 1, At, B1); PG8_BAR;
;             PG8_LDA(At, 0, 1); PG8_STAGE(PG8_SA(0, 0), a2, voffA);
;             PG8_BAR; PG8_WAIT_L(0); PG8_MMA(1, 0, At, B0); PG8_BAR; PG8_SCHED;
;             PG8_STAGE(PG8_SB(0, 1), b2 + hstep, voffB);
;             PG8_WAIT_V(6); PG8_BAR; PG8_MMA(1, 1, At, B1); PG8_BAR;
	s_nop 0
	v_mfma_f32_16x16x32_bf16 v[60:63], v[152:155], v[168:171], 0
	v_mfma_f32_16x16x32_bf16 v[56:59], v[160:163], v[168:171], 0
	v_mfma_f32_16x16x32_bf16 v[44:47], v[152:155], v[176:179], 0
	v_mfma_f32_16x16x32_bf16 v[40:43], v[160:163], v[176:179], 0
	v_mfma_f32_16x16x32_bf16 v[28:31], v[152:155], v[188:191], 0
	v_mfma_f32_16x16x32_bf16 v[24:27], v[160:163], v[188:191], 0
	v_mfma_f32_16x16x32_bf16 v[12:15], v[152:155], v[196:199], 0
	v_mfma_f32_16x16x32_bf16 v[8:11], v[160:163], v[196:199], 0
	v_mfma_f32_16x16x32_bf16 v[60:63], v[156:159], v[172:175], v[60:63]
	v_mfma_f32_16x16x32_bf16 v[56:59], v[164:167], v[172:175], v[56:59]
	v_mfma_f32_16x16x32_bf16 v[44:47], v[156:159], v[184:187], v[44:47]
	v_mfma_f32_16x16x32_bf16 v[40:43], v[164:167], v[184:187], v[40:43]
	v_mfma_f32_16x16x32_bf16 v[28:31], v[156:159], v[192:195], v[28:31]
	v_mfma_f32_16x16x32_bf16 v[24:27], v[164:167], v[192:195], v[24:27]
	v_mfma_f32_16x16x32_bf16 v[12:15], v[156:159], v[200:203], v[12:15]
	v_mfma_f32_16x16x32_bf16 v[8:11], v[164:167], v[200:203], v[8:11]
	v_mfma_f32_16x16x32_bf16 v[52:55], v[204:207], v[168:171], 0
	v_mfma_f32_16x16x32_bf16 v[48:51], v[212:215], v[168:171], 0
	v_mfma_f32_16x16x32_bf16 v[36:39], v[204:207], v[176:179], 0
	v_mfma_f32_16x16x32_bf16 v[32:35], v[212:215], v[176:179], 0
	v_mfma_f32_16x16x32_bf16 v[20:23], v[204:207], v[188:191], 0
	v_mfma_f32_16x16x32_bf16 v[16:19], v[212:215], v[188:191], 0
	v_mfma_f32_16x16x32_bf16 v[4:7], v[204:207], v[196:199], 0
	v_mfma_f32_16x16x32_bf16 v[0:3], v[212:215], v[196:199], 0
	v_mfma_f32_16x16x32_bf16 v[52:55], v[208:211], v[172:175], v[52:55]
	v_mfma_f32_16x16x32_bf16 v[48:51], v[216:219], v[172:175], v[48:51]
	v_mfma_f32_16x16x32_bf16 v[36:39], v[208:211], v[184:187], v[36:39]
	v_mfma_f32_16x16x32_bf16 v[32:35], v[216:219], v[184:187], v[32:35]
	v_mfma_f32_16x16x32_bf16 v[20:23], v[208:211], v[192:195], v[20:23]
	v_mfma_f32_16x16x32_bf16 v[16:19], v[216:219], v[192:195], v[16:19]
	v_mfma_f32_16x16x32_bf16 v[4:7], v[208:211], v[200:203], v[4:7]
	v_mfma_f32_16x16x32_bf16 v[0:3], v[216:219], v[200:203], v[0:3]
	s_nop 0
	s_add_i32 s51, 0, 0x18000
	v_add_u32_e32 v144, s51, v147
	s_barrier
	ds_read_b128 v[152:155], v144
	ds_read_b128 v[156:159], v144 offset:1024
	ds_read_b128 v[160:163], v144 offset:2048
	ds_read_b128 v[164:167], v144 offset:3072
	s_add_u32 s22, s22, 0x4000
	s_addc_u32 s23, s23, 0
	s_mov_b32 m0, s34
	v_lshl_add_u64 v[144:145], s[22:23], 0, v[132:133]
	ds_read_b128 v[168:171], v149 offset:32768
	ds_read_b128 v[172:175], v149 offset:33792
	ds_read_b128 v[176:179], v149 offset:34816
	ds_read_b128 v[184:187], v149 offset:35840
	ds_read_b128 v[188:191], v149 offset:36864
	ds_read_b128 v[192:195], v149 offset:37888
	ds_read_b128 v[196:199], v149 offset:38912
	ds_read_b128 v[200:203], v149 offset:39936
	global_load_lds_dwordx4 v[144:145], off
	v_lshl_add_u64 v[144:145], s[22:23], 0, v[130:131]
	s_mov_b32 m0, s35
	s_nop 0
	global_load_lds_dwordx4 v[144:145], off
	v_add_u32_e32 v253, 0x1c000, v147
	ds_read_b128 v[204:207], v253
	ds_read_b128 v[208:211], v253 offset:1024
	ds_read_b128 v[212:215], v253 offset:2048
	ds_read_b128 v[216:219], v253 offset:3072
	s_waitcnt lgkmcnt(0)
	s_waitcnt vmcnt(8)
	s_barrier
	s_nop 0
	v_mfma_f32_16x16x32_bf16 v[124:127], v[152:155], v[168:171], v[124:127]
	v_mfma_f32_16x16x32_bf16 v[120:123], v[160:163], v[168:171], v[120:123]
	v_mfma_f32_16x16x32_bf16 v[108:111], v[152:155], v[176:179], v[108:111]
	v_mfma_f32_16x16x32_bf16 v[104:107], v[160:163], v[176:179], v[104:107]
	v_mfma_f32_16x16x32_bf16 v[92:95], v[152:155], v[188:191], v[92:95]
	v_mfma_f32_16x16x32_bf16 v[88:91], v[160:163], v[188:191], v[88:91]
	v_mfma_f32_16x16x32_bf16 v[76:79], v[152:155], v[196:199], v[76:79]
	v_mfma_f32_16x16x32_bf16 v[72:75], v[160:163], v[196:199], v[72:75]
	v_mfma_f32_16x16x32_bf16 v[124:127], v[156:159], v[172:175], v[124:127]
	v_mfma_f32_16x16x32_bf16 v[120:123], v[164:167], v[172:175], v[120:123]
	v_mfma_f32_16x16x32_bf16 v[108:111], v[156:159], v[184:187], v[108:111]
	v_mfma_f32_16x16x32_bf16 v[104:107], v[164:167], v[184:187], v[104:107]
	v_mfma_f32_16x16x32_bf16 v[92:95], v[156:159], v[192:195], v[92:95]
	v_mfma_f32_16x16x32_bf16 v[88:91], v[164:167], v[192:195], v[88:91]
	v_mfma_f32_16x16x32_bf16 v[76:79], v[156:159], v[200:203], v[76:79]
	v_mfma_f32_16x16x32_bf16 v[72:75], v[164:167], v[200:203], v[72:75]
	v_mfma_f32_16x16x32_bf16 v[116:119], v[204:207], v[168:171], v[116:119]
	v_mfma_f32_16x16x32_bf16 v[112:115], v[212:215], v[168:171], v[112:115]
	v_mfma_f32_16x16x32_bf16 v[100:103], v[204:207], v[176:179], v[100:103]
	v_mfma_f32_16x16x32_bf16 v[96:99], v[212:215], v[176:179], v[96:99]
	v_mfma_f32_16x16x32_bf16 v[84:87], v[204:207], v[188:191], v[84:87]
	v_mfma_f32_16x16x32_bf16 v[80:83], v[212:215], v[188:191], v[80:83]
	v_mfma_f32_16x16x32_bf16 v[68:71], v[204:207], v[196:199], v[68:71]
	v_mfma_f32_16x16x32_bf16 v[64:67], v[212:215], v[196:199], v[64:67]
	v_mfma_f32_16x16x32_bf16 v[116:119], v[208:211], v[172:175], v[116:119]
	v_mfma_f32_16x16x32_bf16 v[112:115], v[216:219], v[172:175], v[112:115]
	v_mfma_f32_16x16x32_bf16 v[100:103], v[208:211], v[184:187], v[100:103]
	v_mfma_f32_16x16x32_bf16 v[96:99], v[216:219], v[184:187], v[96:99]
	v_mfma_f32_16x16x32_bf16 v[84:87], v[208:211], v[192:195], v[84:87]
	v_mfma_f32_16x16x32_bf16 v[80:83], v[216:219], v[192:195], v[80:83]
	v_mfma_f32_16x16x32_bf16 v[68:71], v[208:211], v[200:203], v[68:71]
	v_mfma_f32_16x16x32_bf16 v[64:67], v[216:219], v[200:203], v[64:67]
	s_nop 0
	s_barrier
; #define PG8_STAGE(bufoff, gbase, voff) do { _Pragma("unroll") for (int _i = 0; _i < 2; ++_i) \
;         __builtin_amdgcn_global_load_lds((const unsigned*)((const char*)(gbase) + (voff)[_i]), (LAS unsigned*)(lds + (bufoff) + ldsw + _i * 8192), 16, 0, 0); } while (0)
; #define PG8_LDA(dst, b, h) do { _Pragma("unroll") for (int m = 0; m < 4; ++m) _Pragma("unroll") for (int k = 0; k < 2; ++k) dst[m][k] = *(const LAS bf16x8*)(lds + PG8_SA(b, h) + aoff + m * 2048 + k * 1024); } while (0)
; #define PG8_LDB(dst, b, h) do { _Pragma("unroll") for (int n = 0; n < 2; ++n) _Pragma("unroll") for (int k = 0; k < 2; ++k) dst[n][k] = *(const LAS bf16x8*)(lds + PG8_SB(b, h) + boff + n * 2048 + k * 1024); } while (0)
; #define PG8_MMA(ai, bj, At, Bt) do { __builtin_amdgcn_s_setprio(1); _Pragma("unroll") for (int m = 0; m < 4; ++m) _Pragma("unroll") for (int n = 0; n < 2; ++n) _Pragma("unroll") for (int k = 0; k < 2; ++k) \
;         acc[ai][bj][m][n] = __builtin_amdgcn_mfma_f32_16x16x32_bf16(Bt[n][k], At[m][k], acc[ai][bj][m][n], 0, 0, 0); __builtin_amdgcn_s_setprio(0); } while (0)
; #define PG8_WAIT_V(n) asm volatile("s_waitcnt vmcnt(" #n ")" ::: "memory")
; #define PG8_WAIT_L(n) asm volatile("s_waitcnt lgkmcnt(" #n ")" ::: "memory")
; #define PG8_BAR __builtin_amdgcn_s_barrier()
; #define PG8_SCHED __builtin_amdgcn_sched_barrier(0)
; template <class Epi>
; __device__ __forceinline__ void gemm_phase(LAS unsigned char* lds, const Gemm g, const StaticOrder& S, const Epi& E) {
;     ...
;             PG8_LDB(B0, 1, 0); PG8_SCHED; PG8_LDA(At, 1, 0); PG8_STAGE(PG8_SA(0, 1), a2 + hstep, voffA);
;             PG8_WAIT_L(8); PG8_BAR; PG8_WAIT_L(0); PG8_MMA(0, 0, At, B0); PG8_BAR; PG8_SCHED;
;             PG8_LDB(B1, 1, 1); PG8_STAGE(PG8_SB(1, 0), b3, voffB);
;             PG8_BAR; PG8_WAIT_L(0); PG8_MMA(0, 1, At, B1); PG8_BAR;
;             PG8_LDA(At, 1, 1); PG8_STAGE(PG8_SA(1, 0), a3, voffA);
;             PG8_BAR; PG8_WAIT_L(0); PG8_MMA(1, 0, At, B0); PG8_BAR; PG8_SCHED;
;             PG8_STAGE(PG8_SB(1, 1), b3 + hstep, voffB);
;             PG8_WAIT_V(6); PG8_BAR; PG8_MMA(1, 1, At, B1); PG8_BAR;
	s_add_i32 s54, 0, 0x1c000
	s_add_u32 s22, s18, 0x160000
	v_add_u32_e32 v144, s54, v147
	s_addc_u32 s23, s19, 0
	s_add_i32 s51, s51, s27
	s_nop 0
	v_lshl_add_u64 v[144:145], s[22:23], 0, v[132:133]
	s_mov_b32 m0, s51
	s_nop 0
	global_load_lds_dwordx4 v[144:145], off
	v_lshl_add_u64 v[144:145], s[22:23], 0, v[130:131]
	s_add_i32 m0, s51, 0x2000
	s_nop 0
	global_load_lds_dwordx4 v[144:145], off
	s_mov_b32 m0, s38
	v_lshl_add_u64 v[144:145], s[20:21], 0, v[132:133]
	ds_read_b128 v[168:171], v149 offset:49152
	ds_read_b128 v[172:175], v149 offset:50176
	ds_read_b128 v[176:179], v149 offset:51200
	ds_read_b128 v[184:187], v149 offset:52224
	ds_read_b128 v[188:191], v149 offset:53248
	ds_read_b128 v[192:195], v149 offset:54272
	ds_read_b128 v[196:199], v149 offset:55296
	ds_read_b128 v[200:203], v149 offset:56320
	global_load_lds_dwordx4 v[144:145], off
	v_lshl_add_u64 v[144:145], s[20:21], 0, v[130:131]
	s_mov_b32 m0, s39
	s_nop 0
	global_load_lds_dwordx4 v[144:145], off
	s_add_u32 s18, s18, 0x164000
	s_addc_u32 s19, s19, 0
	s_add_i32 s20, s54, s27
	v_lshl_add_u64 v[144:145], s[18:19], 0, v[132:133]
	s_mov_b32 m0, s20
	s_nop 0
	global_load_lds_dwordx4 v[144:145], off
	v_lshl_add_u64 v[144:145], s[18:19], 0, v[130:131]
	s_add_i32 m0, s20, 0x2000
	s_nop 0
	global_load_lds_dwordx4 v[144:145], off
	s_waitcnt lgkmcnt(0)
	s_waitcnt vmcnt(8)
	s_barrier
	s_nop 0
	v_mfma_f32_16x16x32_bf16 v[60:63], v[152:155], v[168:171], v[60:63]
	v_mfma_f32_16x16x32_bf16 v[56:59], v[160:163], v[168:171], v[56:59]
	v_mfma_f32_16x16x32_bf16 v[44:47], v[152:155], v[176:179], v[44:47]
	v_mfma_f32_16x16x32_bf16 v[40:43], v[160:163], v[176:179], v[40:43]
	v_mfma_f32_16x16x32_bf16 v[28:31], v[152:155], v[188:191], v[28:31]
	v_mfma_f32_16x16x32_bf16 v[24:27], v[160:163], v[188:191], v[24:27]
	v_mfma_f32_16x16x32_bf16 v[12:15], v[152:155], v[196:199], v[12:15]
	v_mfma_f32_16x16x32_bf16 v[8:11], v[160:163], v[196:199], v[8:11]
	v_mfma_f32_16x16x32_bf16 v[60:63], v[156:159], v[172:175], v[60:63]
	v_mfma_f32_16x16x32_bf16 v[56:59], v[164:167], v[172:175], v[56:59]
	v_mfma_f32_16x16x32_bf16 v[44:47], v[156:159], v[184:187], v[44:47]
	v_mfma_f32_16x16x32_bf16 v[40:43], v[164:167], v[184:187], v[40:43]
	v_mfma_f32_16x16x32_bf16 v[28:31], v[156:159], v[192:195], v[28:31]
	v_mfma_f32_16x16x32_bf16 v[24:27], v[164:167], v[192:195], v[24:27]
	v_mfma_f32_16x16x32_bf16 v[12:15], v[156:159], v[200:203], v[12:15]
	v_mfma_f32_16x16x32_bf16 v[8:11], v[164:167], v[200:203], v[8:11]
	v_mfma_f32_16x16x32_bf16 v[52:55], v[204:207], v[168:171], v[52:55]
	v_mfma_f32_16x16x32_bf16 v[48:51], v[212:215], v[168:171], v[48:51]
	v_mfma_f32_16x16x32_bf16 v[36:39], v[204:207], v[176:179], v[36:39]
	v_mfma_f32_16x16x32_bf16 v[32:35], v[212:215], v[176:179], v[32:35]
	v_mfma_f32_16x16x32_bf16 v[20:23], v[204:207], v[188:191], v[20:23]
	v_mfma_f32_16x16x32_bf16 v[16:19], v[212:215], v[188:191], v[16:19]
	v_mfma_f32_16x16x32_bf16 v[4:7], v[204:207], v[196:199], v[4:7]
	v_mfma_f32_16x16x32_bf16 v[0:3], v[212:215], v[196:199], v[0:3]
	v_mfma_f32_16x16x32_bf16 v[52:55], v[208:211], v[172:175], v[52:55]
	v_mfma_f32_16x16x32_bf16 v[48:51], v[216:219], v[172:175], v[48:51]
	v_mfma_f32_16x16x32_bf16 v[36:39], v[208:211], v[184:187], v[36:39]
	v_mfma_f32_16x16x32_bf16 v[32:35], v[216:219], v[184:187], v[32:35]
	v_mfma_f32_16x16x32_bf16 v[20:23], v[208:211], v[192:195], v[20:23]
	v_mfma_f32_16x16x32_bf16 v[16:19], v[216:219], v[192:195], v[16:19]
	v_mfma_f32_16x16x32_bf16 v[4:7], v[208:211], v[200:203], v[4:7]
	v_mfma_f32_16x16x32_bf16 v[0:3], v[216:219], v[200:203], v[0:3]
	s_nop 0
	s_add_i32 s50, s50, 2
	s_add_u32 s48, s48, 0x2c0000
	s_addc_u32 s49, s49, 0
	s_add_u32 s16, s16, 0x800000
	s_addc_u32 s17, s17, 0
	s_cmp_gt_u32 s50, 29
	s_barrier

; #define PG8_STAGE(bufoff, gbase, voff) do { _Pragma("unroll") for (int _i = 0; _i < 2; ++_i) \
;         __builtin_amdgcn_global_load_lds((const unsigned*)((const char*)(gbase) + (voff)[_i]), (LAS unsigned*)(lds + (bufoff) + ldsw + _i * 8192), 16, 0, 0); } while (0)
; #define PG8_LDA(dst, b, h) do { _Pragma("unroll") for (int m = 0; m < 4; ++m) _Pragma("unroll") for (int k = 0; k < 2; ++k) dst[m][k] = *(const LAS bf16x8*)(lds + PG8_SA(b, h) + aoff + m * 2048 + k * 1024); } while (0)
; #define PG8_LDB(dst, b, h) do { _Pragma("unroll") for (int n = 0; n < 2; ++n) _Pragma("unroll") for (int k = 0; k < 2; ++k) dst[n][k] = *(const LAS bf16x8*)(lds + PG8_SB(b, h) + boff + n * 2048 + k * 1024); } while (0)
; #define PG8_WAIT_V(n) asm volatile("s_waitcnt vmcnt(" #n ")" ::: "memory")
; #define PG8_WAIT_L(n) asm volatile("s_waitcnt lgkmcnt(" #n ")" ::: "memory")
; #define PG8_BAR __builtin_amdgcn_s_barrier()
; #define PG8_SCHED __builtin_amdgcn_sched_barrier(0)
; template <class Epi>
; __device__ __forceinline__ void gemm_phase(LAS unsigned char* lds, const Gemm g, const StaticOrder& S, const Epi& E) {
;     ...
;         const bool has_next = S.next(ui + 1, nxt);
;         const char* nA = has_next ? (const char*)g.A + (size_t)nxt.pm * tstep : cA; const char* nB = has_next ? (const char*)g.Bt + (size_t)nxt.pn * tstep : cB;
;         for (int t = 0; t < nt; t += 2) {
;             const bool last = (t == nt - 2);
;             const char* a1 = cA + (size_t)(t + 1) * kstepA;
;             const char* a2 = last ? nA : cA + (size_t)(t + 2) * kstepA; const char* b2 = last ? nB : cB + (size_t)(t + 2) * kstepB;
;             const char* a3 = a2 + kstepA; const char* b3 = b2 + kstepB;
;             PG8_LDB(B0, 0, 0); PG8_SCHED; PG8_LDA(At, 0, 0); PG8_STAGE(PG8_SA(1, 1), a1 + hstep, voffA);
;             PG8_WAIT_L(8); PG8_BAR; PG8_WAIT_L(0); PG8_MMA(0, 0, At, B0); PG8_BAR; PG8_SCHED;
;             PG8_LDB(B1, 0, 1); PG8_STAGE(PG8_SB(0, 0), b2, voffB);
;             PG8_BAR; PG8_WAIT_L(0); PG8_MMA(0, 1, At, B1); PG8_BAR;
;             PG8_LDA(At, 0, 1); PG8_STAGE(PG8_SA(0, 0), a2, voffA);
;             PG8_BAR; PG8_WAIT_L(0); PG8_MMA(1, 0, At, B0); PG8_BAR; PG8_SCHED;
;             PG8_STAGE(PG8_SB(0, 1), b2 + hstep, voffB);
;             PG8_WAIT_V(6); PG8_BAR; PG8_MMA(1, 1, At, B1); PG8_BAR;
.LBB0_956:
	s_ashr_i32 s15, s14, 31
	v_cmp_lt_i64_e32 vcc, s[16:17], v[142:143]
	s_lshl_b64 s[16:17], s[14:15], 15
	s_add_u32 s16, s2, s16
	s_addc_u32 s17, s3, s17
	s_and_b64 s[18:19], vcc, exec
	s_cselect_b32 s15, s17, s25
	s_cselect_b32 s56, s16, s24
	s_ashr_i32 s13, s12, 31
	s_lshl_b64 s[18:19], s[12:13], 15
	s_add_u32 s18, s34, s18
	s_addc_u32 s19, s35, s19
	s_and_b64 s[26:27], vcc, exec
	s_cselect_b32 s13, s19, s23
	s_cselect_b32 s57, s18, s22
	s_add_u32 s58, s22, 0x80000
	s_addc_u32 s59, s23, 0
	s_add_u32 s22, s24, 0x404000
	v_mov_b32_e32 v0, 0
	s_addc_u32 s23, s25, 0
	s_mov_b32 s60, -2
	ds_read_b128 v[154:157], v151
	ds_read_b128 v[158:161], v151 offset:1024
	ds_read_b128 v[162:165], v151 offset:2048
	ds_read_b128 v[166:169], v151 offset:3072
	s_add_u32 s24, s22, 0x3fc000
	s_addc_u32 s25, s23, 0
	s_cmpk_eq_i32 s60, 0x54
	s_cselect_b32 s28, s56, s24
	s_cselect_b32 s29, s15, s25
	s_cselect_b32 s25, s13, s59
	s_cselect_b32 s24, s57, s58
	s_add_u32 s26, s28, 0x400000
	s_addc_u32 s27, s29, 0
	v_lshl_add_u64 v[146:147], s[22:23], 0, v[138:139]
	s_add_i32 m0, s21, 0xc000
	ds_read_b128 v[170:173], v152
	ds_read_b128 v[174:177], v152 offset:1024
	ds_read_b128 v[184:187], v152 offset:2048
	ds_read_b128 v[188:191], v152 offset:3072
	ds_read_b128 v[192:195], v152 offset:4096
	ds_read_b128 v[196:199], v152 offset:5120
	ds_read_b128 v[200:203], v152 offset:6144
	ds_read_b128 v[204:207], v152 offset:7168
	global_load_lds_dwordx4 v[146:147], off
	v_lshl_add_u64 v[146:147], s[22:23], 0, v[140:141]
	s_add_i32 m0, s21, 0xe000
	s_nop 0
	global_load_lds_dwordx4 v[146:147], off
	ds_read_b128 v[208:211], v153
	ds_read_b128 v[212:215], v153 offset:1024
	ds_read_b128 v[216:219], v153 offset:2048
	ds_read_b128 v[220:223], v153 offset:3072
	s_waitcnt lgkmcnt(0)
	s_waitcnt vmcnt(8)
	s_barrier
	s_nop 0
	v_mfma_f32_16x16x32_bf16 v[124:127], v[154:157], v[170:173], 0
	v_mfma_f32_16x16x32_bf16 v[120:123], v[162:165], v[170:173], 0
	v_mfma_f32_16x16x32_bf16 v[112:115], v[154:157], v[184:187], 0
	v_mfma_f32_16x16x32_bf16 v[104:107], v[162:165], v[184:187], 0
	v_mfma_f32_16x16x32_bf16 v[96:99], v[154:157], v[192:195], 0
	v_mfma_f32_16x16x32_bf16 v[88:91], v[162:165], v[192:195], 0
	v_mfma_f32_16x16x32_bf16 v[80:83], v[154:157], v[200:203], 0
	v_mfma_f32_16x16x32_bf16 v[72:75], v[162:165], v[200:203], 0
	v_mfma_f32_16x16x32_bf16 v[124:127], v[158:161], v[174:177], v[124:127]
	v_mfma_f32_16x16x32_bf16 v[120:123], v[166:169], v[174:177], v[120:123]
	v_mfma_f32_16x16x32_bf16 v[112:115], v[158:161], v[188:191], v[112:115]
	v_mfma_f32_16x16x32_bf16 v[104:107], v[166:169], v[188:191], v[104:107]
	v_mfma_f32_16x16x32_bf16 v[96:99], v[158:161], v[196:199], v[96:99]
	v_mfma_f32_16x16x32_bf16 v[88:91], v[166:169], v[196:199], v[88:91]
	v_mfma_f32_16x16x32_bf16 v[80:83], v[158:161], v[204:207], v[80:83]
	v_mfma_f32_16x16x32_bf16 v[72:75], v[166:169], v[204:207], v[72:75]
	v_mfma_f32_16x16x32_bf16 v[116:119], v[208:211], v[170:173], 0
	v_mfma_f32_16x16x32_bf16 v[108:111], v[216:219], v[170:173], 0
	v_mfma_f32_16x16x32_bf16 v[100:103], v[208:211], v[184:187], 0
	v_mfma_f32_16x16x32_bf16 v[92:95], v[216:219], v[184:187], 0
	v_mfma_f32_16x16x32_bf16 v[84:87], v[208:211], v[192:195], 0
	v_mfma_f32_16x16x32_bf16 v[76:79], v[216:219], v[192:195], 0
	v_mfma_f32_16x16x32_bf16 v[68:71], v[208:211], v[200:203], 0
	v_mfma_f32_16x16x32_bf16 v[64:67], v[216:219], v[200:203], 0
	v_mfma_f32_16x16x32_bf16 v[116:119], v[212:215], v[174:177], v[116:119]
	v_mfma_f32_16x16x32_bf16 v[108:111], v[220:223], v[174:177], v[108:111]
	v_mfma_f32_16x16x32_bf16 v[100:103], v[212:215], v[188:191], v[100:103]
	v_mfma_f32_16x16x32_bf16 v[92:95], v[220:223], v[188:191], v[92:95]
	v_mfma_f32_16x16x32_bf16 v[84:87], v[212:215], v[196:199], v[84:87]
	v_mfma_f32_16x16x32_bf16 v[76:79], v[220:223], v[196:199], v[76:79]
	v_mfma_f32_16x16x32_bf16 v[68:71], v[212:215], v[204:207], v[68:71]
	v_mfma_f32_16x16x32_bf16 v[64:67], v[220:223], v[204:207], v[64:67]
	s_nop 0
	s_barrier
	s_add_i32 s61, s45, s36
	v_lshl_add_u64 v[146:147], s[24:25], 0, v[132:133]
	s_mov_b32 m0, s61
	s_nop 0
	global_load_lds_dwordx4 v[146:147], off
	v_lshl_add_u64 v[146:147], s[24:25], 0, v[136:137]
	s_add_i32 m0, s61, 0x2000
	s_nop 0
	global_load_lds_dwordx4 v[146:147], off
	s_mov_b32 m0, s21
	v_lshl_add_u64 v[146:147], s[28:29], 0, v[130:131]
	ds_read_b128 v[170:173], v152 offset:16384
	ds_read_b128 v[174:177], v152 offset:17408
	ds_read_b128 v[184:187], v152 offset:18432
	ds_read_b128 v[188:191], v152 offset:19456
	ds_read_b128 v[192:195], v152 offset:20480
	ds_read_b128 v[196:199], v152 offset:21504
	ds_read_b128 v[200:203], v152 offset:22528
	ds_read_b128 v[204:207], v152 offset:23552
	global_load_lds_dwordx4 v[146:147], off
	v_lshl_add_u64 v[146:147], s[28:29], 0, v[134:135]
	s_mov_b32 m0, s37
	s_nop 0
	global_load_lds_dwordx4 v[146:147], off
	s_add_u32 s62, s24, 0x4000
	s_addc_u32 s63, s25, 0
	s_add_i32 s61, s48, s36
	v_lshl_add_u64 v[146:147], s[62:63], 0, v[132:133]
	s_mov_b32 m0, s61
	s_nop 0
	global_load_lds_dwordx4 v[146:147], off
	v_lshl_add_u64 v[146:147], s[62:63], 0, v[136:137]
	s_add_i32 m0, s61, 0x2000
	s_nop 0
	global_load_lds_dwordx4 v[146:147], off
	s_waitcnt lgkmcnt(0)
	s_waitcnt vmcnt(8)
	s_barrier
; #define PG8_STAGE(bufoff, gbase, voff) do { _Pragma("unroll") for (int _i = 0; _i < 2; ++_i) \
;         __builtin_amdgcn_global_load_lds((const unsigned*)((const char*)(gbase) + (voff)[_i]), (LAS unsigned*)(lds + (bufoff) + ldsw + _i * 8192), 16, 0, 0); } while (0)
; #define PG8_LDA(dst, b, h) do { _Pragma("unroll") for (int m = 0; m < 4; ++m) _Pragma("unroll") for (int k = 0; k < 2; ++k) dst[m][k] = *(const LAS bf16x8*)(lds + PG8_SA(b, h) + aoff + m * 2048 + k * 1024); } while (0)
; #define PG8_LDB(dst, b, h) do { _Pragma("unroll") for (int n = 0; n < 2; ++n) _Pragma("unroll") for (int k = 0; k < 2; ++k) dst[n][k] = *(const LAS bf16x8*)(lds + PG8_SB(b, h) + boff + n * 2048 + k * 1024); } while (0)
; #define PG8_MMA(ai, bj, At, Bt) do { __builtin_amdgcn_s_setprio(1); _Pragma("unroll") for (int m = 0; m < 4; ++m) _Pragma("unroll") for (int n = 0; n < 2; ++n) _Pragma("unroll") for (int k = 0; k < 2; ++k) \
;         acc[ai][bj][m][n] = __builtin_amdgcn_mfma_f32_16x16x32_bf16(Bt[n][k], At[m][k], acc[ai][bj][m][n], 0, 0, 0); __builtin_amdgcn_s_setprio(0); } while (0)
; #define PG8_WAIT_V(n) asm volatile("s_waitcnt vmcnt(" #n ")" ::: "memory")
; #define PG8_WAIT_L(n) asm volatile("s_waitcnt lgkmcnt(" #n ")" ::: "memory")
; #define PG8_BAR __builtin_amdgcn_s_barrier()
; #define PG8_SCHED __builtin_amdgcn_sched_barrier(0)
; template <class Epi>
; __device__ __forceinline__ void gemm_phase(LAS unsigned char* lds, const Gemm g, const StaticOrder& S, const Epi& E) {
;     ...
;             PG8_BAR; PG8_WAIT_L(0); PG8_MMA(1, 0, At, B0); PG8_BAR; PG8_SCHED;
;             PG8_STAGE(PG8_SB(0, 1), b2 + hstep, voffB);
;             PG8_WAIT_V(6); PG8_BAR; PG8_MMA(1, 1, At, B1); PG8_BAR;
;             PG8_LDB(B0, 1, 0); PG8_SCHED; PG8_LDA(At, 1, 0); PG8_STAGE(PG8_SA(0, 1), a2 + hstep, voffA);
;             PG8_WAIT_L(8); PG8_BAR; PG8_WAIT_L(0); PG8_MMA(0, 0, At, B0); PG8_BAR; PG8_SCHED;
;             PG8_LDB(B1, 1, 1); PG8_STAGE(PG8_SB(1, 0), b3, voffB);
;             PG8_BAR; PG8_WAIT_L(0); PG8_MMA(0, 1, At, B1); PG8_BAR;
;             PG8_LDA(At, 1, 1); PG8_STAGE(PG8_SA(1, 0), a3, voffA);
;             PG8_BAR; PG8_WAIT_L(0); PG8_MMA(1, 0, At, B0); PG8_BAR; PG8_SCHED;
	s_nop 0
	v_mfma_f32_16x16x32_bf16 v[60:63], v[154:157], v[170:173], 0
	v_mfma_f32_16x16x32_bf16 v[56:59], v[162:165], v[170:173], 0
	v_mfma_f32_16x16x32_bf16 v[52:55], v[154:157], v[184:187], 0
	v_mfma_f32_16x16x32_bf16 v[44:47], v[162:165], v[184:187], 0
	v_mfma_f32_16x16x32_bf16 v[36:39], v[154:157], v[192:195], 0
	v_mfma_f32_16x16x32_bf16 v[28:31], v[162:165], v[192:195], 0
	v_mfma_f32_16x16x32_bf16 v[20:23], v[154:157], v[200:203], 0
	v_mfma_f32_16x16x32_bf16 v[12:15], v[162:165], v[200:203], 0
	v_mfma_f32_16x16x32_bf16 v[60:63], v[158:161], v[174:177], v[60:63]
	v_mfma_f32_16x16x32_bf16 v[56:59], v[166:169], v[174:177], v[56:59]
	v_mfma_f32_16x16x32_bf16 v[52:55], v[158:161], v[188:191], v[52:55]
	v_mfma_f32_16x16x32_bf16 v[44:47], v[166:169], v[188:191], v[44:47]
	v_mfma_f32_16x16x32_bf16 v[36:39], v[158:161], v[196:199], v[36:39]
	v_mfma_f32_16x16x32_bf16 v[28:31], v[166:169], v[196:199], v[28:31]
	v_mfma_f32_16x16x32_bf16 v[20:23], v[158:161], v[204:207], v[20:23]
	v_mfma_f32_16x16x32_bf16 v[12:15], v[166:169], v[204:207], v[12:15]
	v_mfma_f32_16x16x32_bf16 v[48:51], v[208:211], v[170:173], 0
	v_mfma_f32_16x16x32_bf16 v[40:43], v[216:219], v[170:173], 0
	v_mfma_f32_16x16x32_bf16 v[32:35], v[208:211], v[184:187], 0
	v_mfma_f32_16x16x32_bf16 v[24:27], v[216:219], v[184:187], 0
	v_mfma_f32_16x16x32_bf16 v[16:19], v[208:211], v[192:195], 0
	v_mfma_f32_16x16x32_bf16 v[8:11], v[216:219], v[192:195], 0
	v_mfma_f32_16x16x32_bf16 v[4:7], v[208:211], v[200:203], 0
	v_mfma_f32_16x16x32_bf16 v[0:3], v[216:219], v[200:203], 0
	v_mfma_f32_16x16x32_bf16 v[48:51], v[212:215], v[174:177], v[48:51]
	v_mfma_f32_16x16x32_bf16 v[40:43], v[220:223], v[174:177], v[40:43]
	v_mfma_f32_16x16x32_bf16 v[32:35], v[212:215], v[188:191], v[32:35]
	v_mfma_f32_16x16x32_bf16 v[24:27], v[220:223], v[188:191], v[24:27]
	v_mfma_f32_16x16x32_bf16 v[16:19], v[212:215], v[196:199], v[16:19]
	v_mfma_f32_16x16x32_bf16 v[8:11], v[220:223], v[196:199], v[8:11]
	v_mfma_f32_16x16x32_bf16 v[4:7], v[212:215], v[204:207], v[4:7]
	v_mfma_f32_16x16x32_bf16 v[0:3], v[220:223], v[204:207], v[0:3]
	s_nop 0
	s_add_i32 s61, 0, 0x18000
	v_add_u32_e32 v146, s61, v149
	s_barrier
	ds_read_b128 v[154:157], v146
	ds_read_b128 v[158:161], v146 offset:1024
	ds_read_b128 v[162:165], v146 offset:2048
	ds_read_b128 v[166:169], v146 offset:3072
	s_add_u32 s28, s28, 0x4000
	s_addc_u32 s29, s29, 0
	s_mov_b32 m0, s38
	v_lshl_add_u64 v[146:147], s[28:29], 0, v[130:131]
	ds_read_b128 v[170:173], v152 offset:32768
	ds_read_b128 v[174:177], v152 offset:33792
	ds_read_b128 v[184:187], v152 offset:34816
	ds_read_b128 v[188:191], v152 offset:35840
	ds_read_b128 v[192:195], v152 offset:36864
	ds_read_b128 v[196:199], v152 offset:37888
	ds_read_b128 v[200:203], v152 offset:38912
	ds_read_b128 v[204:207], v152 offset:39936
	global_load_lds_dwordx4 v[146:147], off
	v_lshl_add_u64 v[146:147], s[28:29], 0, v[134:135]
	s_mov_b32 m0, s39
	s_nop 0
	global_load_lds_dwordx4 v[146:147], off
	v_add_u32_e32 v253, 0x1c000, v149
	ds_read_b128 v[208:211], v253
	ds_read_b128 v[212:215], v253 offset:1024
	ds_read_b128 v[216:219], v253 offset:2048
	ds_read_b128 v[220:223], v253 offset:3072
	s_waitcnt lgkmcnt(0)
	s_waitcnt vmcnt(8)
	s_barrier
	s_nop 0
	v_mfma_f32_16x16x32_bf16 v[124:127], v[154:157], v[170:173], v[124:127]
	v_mfma_f32_16x16x32_bf16 v[120:123], v[162:165], v[170:173], v[120:123]
	v_mfma_f32_16x16x32_bf16 v[112:115], v[154:157], v[184:187], v[112:115]
	v_mfma_f32_16x16x32_bf16 v[104:107], v[162:165], v[184:187], v[104:107]
	v_mfma_f32_16x16x32_bf16 v[96:99], v[154:157], v[192:195], v[96:99]
	v_mfma_f32_16x16x32_bf16 v[88:91], v[162:165], v[192:195], v[88:91]
	v_mfma_f32_16x16x32_bf16 v[80:83], v[154:157], v[200:203], v[80:83]
	v_mfma_f32_16x16x32_bf16 v[72:75], v[162:165], v[200:203], v[72:75]
	v_mfma_f32_16x16x32_bf16 v[124:127], v[158:161], v[174:177], v[124:127]
	v_mfma_f32_16x16x32_bf16 v[120:123], v[166:169], v[174:177], v[120:123]
	v_mfma_f32_16x16x32_bf16 v[112:115], v[158:161], v[188:191], v[112:115]
	v_mfma_f32_16x16x32_bf16 v[104:107], v[166:169], v[188:191], v[104:107]
	v_mfma_f32_16x16x32_bf16 v[96:99], v[158:161], v[196:199], v[96:99]
	v_mfma_f32_16x16x32_bf16 v[88:91], v[166:169], v[196:199], v[88:91]
	v_mfma_f32_16x16x32_bf16 v[80:83], v[158:161], v[204:207], v[80:83]
	v_mfma_f32_16x16x32_bf16 v[72:75], v[166:169], v[204:207], v[72:75]
	v_mfma_f32_16x16x32_bf16 v[116:119], v[208:211], v[170:173], v[116:119]
	v_mfma_f32_16x16x32_bf16 v[108:111], v[216:219], v[170:173], v[108:111]
	v_mfma_f32_16x16x32_bf16 v[100:103], v[208:211], v[184:187], v[100:103]
	v_mfma_f32_16x16x32_bf16 v[92:95], v[216:219], v[184:187], v[92:95]
	v_mfma_f32_16x16x32_bf16 v[84:87], v[208:211], v[192:195], v[84:87]
	v_mfma_f32_16x16x32_bf16 v[76:79], v[216:219], v[192:195], v[76:79]
	v_mfma_f32_16x16x32_bf16 v[68:71], v[208:211], v[200:203], v[68:71]
	v_mfma_f32_16x16x32_bf16 v[64:67], v[216:219], v[200:203], v[64:67]
	v_mfma_f32_16x16x32_bf16 v[116:119], v[212:215], v[174:177], v[116:119]
	v_mfma_f32_16x16x32_bf16 v[108:111], v[220:223], v[174:177], v[108:111]
	v_mfma_f32_16x16x32_bf16 v[100:103], v[212:215], v[188:191], v[100:103]
	v_mfma_f32_16x16x32_bf16 v[92:95], v[220:223], v[188:191], v[92:95]
	v_mfma_f32_16x16x32_bf16 v[84:87], v[212:215], v[196:199], v[84:87]
	v_mfma_f32_16x16x32_bf16 v[76:79], v[220:223], v[196:199], v[76:79]
	v_mfma_f32_16x16x32_bf16 v[68:71], v[212:215], v[204:207], v[68:71]
	v_mfma_f32_16x16x32_bf16 v[64:67], v[220:223], v[204:207], v[64:67]
	s_nop 0
	s_barrier
; #define PG8_STAGE(bufoff, gbase, voff) do { _Pragma("unroll") for (int _i = 0; _i < 2; ++_i) \
;         __builtin_amdgcn_global_load_lds((const unsigned*)((const char*)(gbase) + (voff)[_i]), (LAS unsigned*)(lds + (bufoff) + ldsw + _i * 8192), 16, 0, 0); } while (0)
; #define PG8_LDA(dst, b, h) do { _Pragma("unroll") for (int m = 0; m < 4; ++m) _Pragma("unroll") for (int k = 0; k < 2; ++k) dst[m][k] = *(const LAS bf16x8*)(lds + PG8_SA(b, h) + aoff + m * 2048 + k * 1024); } while (0)
; #define PG8_LDB(dst, b, h) do { _Pragma("unroll") for (int n = 0; n < 2; ++n) _Pragma("unroll") for (int k = 0; k < 2; ++k) dst[n][k] = *(const LAS bf16x8*)(lds + PG8_SB(b, h) + boff + n * 2048 + k * 1024); } while (0)
; #define PG8_MMA(ai, bj, At, Bt) do { __builtin_amdgcn_s_setprio(1); _Pragma("unroll") for (int m = 0; m < 4; ++m) _Pragma("unroll") for (int n = 0; n < 2; ++n) _Pragma("unroll") for (int k = 0; k < 2; ++k) \
;         acc[ai][bj][m][n] = __builtin_amdgcn_mfma_f32_16x16x32_bf16(Bt[n][k], At[m][k], acc[ai][bj][m][n], 0, 0, 0); __builtin_amdgcn_s_setprio(0); } while (0)
; #define PG8_WAIT_V(n) asm volatile("s_waitcnt vmcnt(" #n ")" ::: "memory")
; #define PG8_WAIT_L(n) asm volatile("s_waitcnt lgkmcnt(" #n ")" ::: "memory")
; #define PG8_BAR __builtin_amdgcn_s_barrier()
; #define PG8_SCHED __builtin_amdgcn_sched_barrier(0)
; template <class Epi>
; __device__ __forceinline__ void gemm_phase(LAS unsigned char* lds, const Gemm g, const StaticOrder& S, const Epi& E) {
;     ...
;             PG8_LDB(B0, 1, 0); PG8_SCHED; PG8_LDA(At, 1, 0); PG8_STAGE(PG8_SA(0, 1), a2 + hstep, voffA);
;             PG8_WAIT_L(8); PG8_BAR; PG8_WAIT_L(0); PG8_MMA(0, 0, At, B0); PG8_BAR; PG8_SCHED;
;             PG8_LDB(B1, 1, 1); PG8_STAGE(PG8_SB(1, 0), b3, voffB);
;             PG8_BAR; PG8_WAIT_L(0); PG8_MMA(0, 1, At, B1); PG8_BAR;
;             PG8_LDA(At, 1, 1); PG8_STAGE(PG8_SA(1, 0), a3, voffA);
;             PG8_BAR; PG8_WAIT_L(0); PG8_MMA(1, 0, At, B0); PG8_BAR; PG8_SCHED;
;             PG8_STAGE(PG8_SB(1, 1), b3 + hstep, voffB);
;             PG8_WAIT_V(6); PG8_BAR; PG8_MMA(1, 1, At, B1); PG8_BAR;
	s_add_i32 s62, 0, 0x1c000
	s_add_u32 s28, s24, 0x40000
	v_add_u32_e32 v146, s62, v149
	s_addc_u32 s29, s25, 0
	s_add_i32 s61, s61, s36
	s_nop 0
	v_lshl_add_u64 v[146:147], s[28:29], 0, v[132:133]
	s_mov_b32 m0, s61
	s_nop 0
	global_load_lds_dwordx4 v[146:147], off
	v_lshl_add_u64 v[146:147], s[28:29], 0, v[136:137]
	s_add_i32 m0, s61, 0x2000
	s_nop 0
	global_load_lds_dwordx4 v[146:147], off
	s_mov_b32 m0, s41
	v_lshl_add_u64 v[146:147], s[26:27], 0, v[130:131]
	ds_read_b128 v[170:173], v152 offset:49152
	ds_read_b128 v[174:177], v152 offset:50176
	ds_read_b128 v[184:187], v152 offset:51200
	ds_read_b128 v[188:191], v152 offset:52224
	ds_read_b128 v[192:195], v152 offset:53248
	ds_read_b128 v[196:199], v152 offset:54272
	ds_read_b128 v[200:203], v152 offset:55296
	ds_read_b128 v[204:207], v152 offset:56320
	global_load_lds_dwordx4 v[146:147], off
	v_lshl_add_u64 v[146:147], s[26:27], 0, v[134:135]
	s_mov_b32 m0, s42
	s_nop 0
	global_load_lds_dwordx4 v[146:147], off
	s_add_u32 s24, s24, 0x44000
	s_addc_u32 s25, s25, 0
	s_add_i32 s26, s62, s36
	v_lshl_add_u64 v[146:147], s[24:25], 0, v[132:133]
	s_mov_b32 m0, s26
	s_nop 0
	global_load_lds_dwordx4 v[146:147], off
	v_lshl_add_u64 v[146:147], s[24:25], 0, v[136:137]
	s_add_i32 m0, s26, 0x2000
	s_nop 0
	global_load_lds_dwordx4 v[146:147], off
	s_waitcnt lgkmcnt(0)
	s_waitcnt vmcnt(8)
	s_barrier
	s_nop 0
	v_mfma_f32_16x16x32_bf16 v[60:63], v[154:157], v[170:173], v[60:63]
	v_mfma_f32_16x16x32_bf16 v[56:59], v[162:165], v[170:173], v[56:59]
	v_mfma_f32_16x16x32_bf16 v[52:55], v[154:157], v[184:187], v[52:55]
	v_mfma_f32_16x16x32_bf16 v[44:47], v[162:165], v[184:187], v[44:47]
	v_mfma_f32_16x16x32_bf16 v[36:39], v[154:157], v[192:195], v[36:39]
	v_mfma_f32_16x16x32_bf16 v[28:31], v[162:165], v[192:195], v[28:31]
	v_mfma_f32_16x16x32_bf16 v[20:23], v[154:157], v[200:203], v[20:23]
	v_mfma_f32_16x16x32_bf16 v[12:15], v[162:165], v[200:203], v[12:15]
	v_mfma_f32_16x16x32_bf16 v[60:63], v[158:161], v[174:177], v[60:63]
	v_mfma_f32_16x16x32_bf16 v[56:59], v[166:169], v[174:177], v[56:59]
	v_mfma_f32_16x16x32_bf16 v[52:55], v[158:161], v[188:191], v[52:55]
	v_mfma_f32_16x16x32_bf16 v[44:47], v[166:169], v[188:191], v[44:47]
	v_mfma_f32_16x16x32_bf16 v[36:39], v[158:161], v[196:199], v[36:39]
	v_mfma_f32_16x16x32_bf16 v[28:31], v[166:169], v[196:199], v[28:31]
	v_mfma_f32_16x16x32_bf16 v[20:23], v[158:161], v[204:207], v[20:23]
	v_mfma_f32_16x16x32_bf16 v[12:15], v[166:169], v[204:207], v[12:15]
	v_mfma_f32_16x16x32_bf16 v[48:51], v[208:211], v[170:173], v[48:51]
	v_mfma_f32_16x16x32_bf16 v[40:43], v[216:219], v[170:173], v[40:43]
	v_mfma_f32_16x16x32_bf16 v[32:35], v[208:211], v[184:187], v[32:35]
	v_mfma_f32_16x16x32_bf16 v[24:27], v[216:219], v[184:187], v[24:27]
	v_mfma_f32_16x16x32_bf16 v[16:19], v[208:211], v[192:195], v[16:19]
	v_mfma_f32_16x16x32_bf16 v[8:11], v[216:219], v[192:195], v[8:11]
	v_mfma_f32_16x16x32_bf16 v[4:7], v[208:211], v[200:203], v[4:7]
	v_mfma_f32_16x16x32_bf16 v[0:3], v[216:219], v[200:203], v[0:3]
	v_mfma_f32_16x16x32_bf16 v[48:51], v[212:215], v[174:177], v[48:51]
	v_mfma_f32_16x16x32_bf16 v[40:43], v[220:223], v[174:177], v[40:43]
	v_mfma_f32_16x16x32_bf16 v[32:35], v[212:215], v[188:191], v[32:35]
	v_mfma_f32_16x16x32_bf16 v[24:27], v[220:223], v[188:191], v[24:27]
	v_mfma_f32_16x16x32_bf16 v[16:19], v[212:215], v[196:199], v[16:19]
	v_mfma_f32_16x16x32_bf16 v[8:11], v[220:223], v[196:199], v[8:11]
	v_mfma_f32_16x16x32_bf16 v[4:7], v[212:215], v[204:207], v[4:7]
	v_mfma_f32_16x16x32_bf16 v[0:3], v[220:223], v[204:207], v[0:3]
	s_nop 0
	s_add_i32 s60, s60, 2
	s_add_u32 s58, s58, 0x80000
	s_addc_u32 s59, s59, 0
	s_add_u32 s22, s22, 0x800000
	s_addc_u32 s23, s23, 0
	s_cmpk_gt_u32 s60, 0x55
	s_barrier
